# MLA: MFMA-first tile head (the first exp group moves behind the first QK MFMA), on top of static priority + interleaved max chain
# baseline (speedup 1.0000x reference)
; __device__ __forceinline__ void finishSM9(f32x16& p0, f32x16& p1, float alpha, float& l_reg, v8i32& p8) {
; #pragma unroll
;   for (int r = 0; r < 16; ++r) { p0[r] = __builtin_amdgcn_exp2f(p0[r]); p1[r] = __builtin_amdgcn_exp2f(p1[r]); }
;   float ps = 0;
; #pragma unroll
;   for (int r = 0; r < 16; ++r) ps += p0[r];
; #pragma unroll
;   for (int r = 0; r < 16; ++r) ps += p1[r];
;   { auto rr = __builtin_amdgcn_permlane32_swap(__float_as_uint(ps), __float_as_uint(ps), false, false);
;     ps = __uint_as_float(rr[0]) + __uint_as_float(rr[1]); }
;   l_reg = l_reg * alpha + ps;
; #pragma unroll
;   for (int g = 0; g < 4; ++g) {
;     int w = __builtin_amdgcn_cvt_pk_fp8_f32(p0[4 * g], p0[4 * g + 1], 0, false); p8[g] = __builtin_amdgcn_cvt_pk_fp8_f32(p0[4 * g + 2], p0[4 * g + 3], w, true);
;     int u = __builtin_amdgcn_cvt_pk_fp8_f32(p1[4 * g], p1[4 * g + 1], 0, false); p8[4 + g] = __builtin_amdgcn_cvt_pk_fp8_f32(p1[4 * g + 2], p1[4 * g + 3], u, true); }
; }
; __device__ __forceinline__ void pv8(f32x16* o, const char* Vt, const v8i32 p8, int r32, int hi) {
;   const int sw = (r32 >> 2) & 3, a0 = r32 * 64 + (((hi * 2) ^ sw) << 4), a1 = r32 * 64 + (((hi * 2 + 1) ^ sw) << 4);
; #pragma unroll
;   for (int d0 = 0; d0 < 4; ++d0) {
;     const v8i32 vf = cat8(*reinterpret_cast<const v4i32*>(Vt + d0 * 2048 + a0), *reinterpret_cast<const v4i32*>(Vt + d0 * 2048 + a1));
;     o[d0] = __builtin_amdgcn_mfma_scale_f32_32x32x64_f8f6f4(p8, vf, o[d0], 0, 0, 0, 127, 0, 127); }
; }
; __device__ __forceinline__ void qkt9(f32x16& p0, f32x16& p1, const char* Kn, const char* Kr, const v8i32* qf, const float init, int r32, int hi) {
; #pragma unroll
;   for (int r = 0; r < 16; ++r) { p0[r] = init; p1[r] = init; }
; #pragma unroll
;   for (int s = 0; s < 2; ++s) { const int c0 = s * 4 + hi * 2;
;     const v8i32 a0 = cat8(*reinterpret_cast<const v4i32*>(Kn + KN8SW(r32, c0)), *reinterpret_cast<const v4i32*>(Kn + KN8SW(r32, c0 + 1)));
;     const v8i32 a1 = cat8(*reinterpret_cast<const v4i32*>(Kn + 4096 + KN8SW(r32, c0)), *reinterpret_cast<const v4i32*>(Kn + 4096 + KN8SW(r32, c0 + 1)));
;     p0 = __builtin_amdgcn_mfma_scale_f32_32x32x64_f8f6f4(a0, qf[s], p0, 0, 0, 0, 127, 0, 124);
;     p1 = __builtin_amdgcn_mfma_scale_f32_32x32x64_f8f6f4(a1, qf[s], p1, 0, 0, 0, 127, 0, 124); }
;   { const int c0 = hi * 2;
.LBB0_1321:
	ds_read_b128 v[114:117], v215 offset:24576
	ds_read_b128 v[118:121], v216 offset:24576
	ds_read_b128 v[222:225], v215 offset:28672
	ds_read_b128 v[226:229], v216 offset:28672
	s_add_i32 m0, s98, 0xa800
	s_nop 0
	global_load_lds_dwordx4 v176, s[18:19]
	s_add_i32 m0, s98, 0xc800
	s_nop 0
	global_load_lds_dwordx4 v178, s[16:17]
	s_add_i32 m0, s98, 0xe800
	s_nop 0
	global_load_lds_dwordx4 v[180:181], off
	s_waitcnt lgkmcnt(2)
	v_mfma_scale_f32_32x32x64_f8f6f4 v[114:129], v[114:121], v[146:153], v[230:245], v194, v193 op_sel_hi:[0,0,0]
	v_exp_f32_e32 v0, v82
	v_exp_f32_e32 v177, v83
	v_exp_f32_e32 v179, v84
	v_exp_f32_e32 v254, v85
	v_add_f32_e32 v219, v0, v177
	v_cvt_pk_fp8_f32 v246, v0, v177
	v_add_f32_e32 v219, v179, v219
	v_add_f32_e32 v219, v254, v219
	v_cvt_pk_fp8_f32 v246, v179, v254 op_sel:[0,0,1]
	v_exp_f32_e32 v0, v86
	v_exp_f32_e32 v177, v87
	v_exp_f32_e32 v179, v88
	v_exp_f32_e32 v254, v89
	v_add_f32_e32 v219, v0, v219
	v_add_f32_e32 v219, v177, v219
	v_cvt_pk_fp8_f32 v247, v0, v177
	v_add_f32_e32 v219, v179, v219
	v_add_f32_e32 v219, v254, v219
	v_cvt_pk_fp8_f32 v247, v179, v254 op_sel:[0,0,1]
	ds_read_b128 v[82:85], v213 offset:24576
	ds_read_b128 v[86:89], v214 offset:24576
	s_waitcnt lgkmcnt(2)
	v_mfma_scale_f32_32x32x64_f8f6f4 v[98:113], v[222:229], v[146:153], v[230:245], v194, v193 op_sel_hi:[0,0,0]
	ds_read_b128 v[222:225], v213 offset:28672
	ds_read_b128 v[226:229], v214 offset:28672
	v_exp_f32_e32 v0, v90
	v_exp_f32_e32 v177, v91
	v_exp_f32_e32 v179, v92
	v_exp_f32_e32 v254, v93
	v_add_f32_e32 v219, v0, v219
	v_add_f32_e32 v219, v177, v219
	v_cvt_pk_fp8_f32 v248, v0, v177
	v_add_f32_e32 v219, v179, v219
	v_add_f32_e32 v219, v254, v219
	v_cvt_pk_fp8_f32 v248, v179, v254 op_sel:[0,0,1]
	v_exp_f32_e32 v0, v94
	v_exp_f32_e32 v177, v95
	v_exp_f32_e32 v179, v96
	v_exp_f32_e32 v254, v97
	v_add_f32_e32 v219, v0, v219
	v_add_f32_e32 v219, v177, v219
	v_cvt_pk_fp8_f32 v249, v0, v177
	v_add_f32_e32 v219, v179, v219
	v_add_f32_e32 v219, v254, v219
	v_cvt_pk_fp8_f32 v249, v179, v254 op_sel:[0,0,1]
	ds_read_b128 v[90:93], v185 offset:36864
	ds_read_b128 v[94:97], v186 offset:36864
	s_waitcnt lgkmcnt(4)
	v_mfma_scale_f32_32x32x64_f8f6f4 v[114:129], v[82:89], v[138:145], v[114:129], v194, v193 op_sel_hi:[0,0,0]
	v_exp_f32_e32 v0, v66
	v_exp_f32_e32 v177, v67
	v_exp_f32_e32 v179, v68
	v_exp_f32_e32 v254, v69
	v_add_f32_e32 v219, v0, v219
	v_add_f32_e32 v219, v177, v219
	v_cvt_pk_fp8_f32 v250, v0, v177
	v_add_f32_e32 v219, v179, v219
	v_add_f32_e32 v219, v254, v219
	v_cvt_pk_fp8_f32 v250, v179, v254 op_sel:[0,0,1]
	s_waitcnt lgkmcnt(2)
	v_mfma_scale_f32_32x32x64_f8f6f4 v[98:113], v[222:229], v[138:145], v[98:113], v194, v193 op_sel_hi:[0,0,0]
	ds_read_b128 v[222:225], v185 offset:38912
	ds_read_b128 v[226:229], v186 offset:38912
	v_exp_f32_e32 v0, v70
	v_exp_f32_e32 v177, v71
	v_exp_f32_e32 v179, v72
	v_exp_f32_e32 v254, v73
	v_add_f32_e32 v219, v0, v219
	v_add_f32_e32 v219, v177, v219
	v_cvt_pk_fp8_f32 v251, v0, v177
	v_add_f32_e32 v219, v179, v219
	v_add_f32_e32 v219, v254, v219
	v_cvt_pk_fp8_f32 v251, v179, v254 op_sel:[0,0,1]
	v_exp_f32_e32 v0, v74
	v_exp_f32_e32 v177, v75
	v_exp_f32_e32 v179, v76
	v_exp_f32_e32 v254, v77
	v_add_f32_e32 v219, v0, v219
	v_add_f32_e32 v219, v177, v219
	v_cvt_pk_fp8_f32 v252, v0, v177
	v_add_f32_e32 v219, v179, v219
	v_add_f32_e32 v219, v254, v219
	v_cvt_pk_fp8_f32 v252, v179, v254 op_sel:[0,0,1]
	s_waitcnt lgkmcnt(2)
	v_mfma_scale_f32_32x32x64_f8f6f4 v[114:129], v[90:97], v[130:137], v[114:129], v194, v193 op_sel_hi:[0,0,0]
	v_exp_f32_e32 v0, v78
	v_exp_f32_e32 v177, v79
	v_exp_f32_e32 v179, v80
	v_exp_f32_e32 v254, v81
	v_add_f32_e32 v219, v0, v219
	v_add_f32_e32 v219, v177, v219
	v_cvt_pk_fp8_f32 v253, v0, v177
	v_add_f32_e32 v219, v179, v219
	v_add_f32_e32 v219, v254, v219
	v_cvt_pk_fp8_f32 v253, v179, v254 op_sel:[0,0,1]
	ds_read_b128 v[90:93], v185 offset:0
	ds_read_b128 v[94:97], v186 offset:0
	ds_read_b128 v[82:85], v185 offset:2048
	ds_read_b128 v[86:89], v186 offset:2048
	ds_read_b128 v[74:77], v185 offset:4096
	ds_read_b128 v[78:81], v186 offset:4096
	ds_read_b128 v[66:69], v185 offset:6144
	ds_read_b128 v[70:73], v186 offset:6144
	s_waitcnt lgkmcnt(8)
	v_mfma_scale_f32_32x32x64_f8f6f4 v[98:113], v[222:229], v[130:137], v[98:113], v194, v193 op_sel_hi:[0,0,0]
	v_mov_b32_e32 v0, v219
	s_nop 1
	v_permlane32_swap_b32_e32 v219, v0
	v_add_f32_e32 v219, v219, v0
	v_fma_f32 v209, v209, v218, v219
	v_add_u32_e32 v176, 0x2000, v176
	v_add_u32_e32 v178, 0x20000, v178
	s_mov_b64 s[20:21], 0x1000
	v_lshl_add_u64 v[180:181], v[180:181], 0, s[20:21]
	v_max_f32_e32 v177, v114, v115
	v_max3_f32 v177, v177, v116, v117
	v_max3_f32 v177, v177, v118, v119
	v_max3_f32 v177, v177, v120, v121
	v_max3_f32 v177, v177, v122, v123
	v_max3_f32 v177, v177, v124, v125
	v_max3_f32 v177, v177, v126, v127
	v_max3_f32 v177, v177, v128, v129
	s_waitcnt lgkmcnt(6)
	v_mfma_scale_f32_32x32x64_f8f6f4 v[50:65], v[246:253], v[90:97], v[50:65], v194, v194 op_sel_hi:[0,0,0]
	v_max_f32_e32 v0, v98, v99
	v_max3_f32 v0, v0, v100, v101
	v_max3_f32 v0, v0, v102, v103
	s_waitcnt lgkmcnt(4)
	v_mfma_scale_f32_32x32x64_f8f6f4 v[34:49], v[246:253], v[82:89], v[34:49], v194, v194 op_sel_hi:[0,0,0]
	v_max3_f32 v0, v0, v104, v105
	v_max3_f32 v0, v0, v106, v107
	v_max3_f32 v0, v0, v108, v109
	s_waitcnt lgkmcnt(2)
	v_mfma_scale_f32_32x32x64_f8f6f4 v[18:33], v[246:253], v[74:81], v[18:33], v194, v194 op_sel_hi:[0,0,0]
	v_max3_f32 v0, v0, v110, v111
	v_max3_f32 v0, v0, v112, v113
	v_max_f32_e32 v177, v177, v0
	v_mov_b32_e32 v0, v177
	v_mov_b32_e32 v221, 1.0
	s_waitcnt lgkmcnt(0)
	v_mfma_scale_f32_32x32x64_f8f6f4 v[2:17], v[246:253], v[66:73], v[2:17], v194, v194 op_sel_hi:[0,0,0]
	s_waitcnt vmcnt(0)
	s_waitcnt lgkmcnt(0)
	s_barrier
	v_permlane32_swap_b32_e32 v177, v0
	v_max_f32_e32 v177, v177, v0
	v_cmp_ge_f32_e32 vcc, s90, v177
	s_cmp_eq_u64 vcc, exec
	s_cbranch_scc0 .Lmla_h0_newmax
; __device__ __forceinline__ void finishSM9(f32x16& p0, f32x16& p1, float alpha, float& l_reg, v8i32& p8) {
; #pragma unroll
;   for (int r = 0; r < 16; ++r) { p0[r] = __builtin_amdgcn_exp2f(p0[r]); p1[r] = __builtin_amdgcn_exp2f(p1[r]); }
;   float ps = 0;
; #pragma unroll
;   for (int r = 0; r < 16; ++r) ps += p0[r];
; #pragma unroll
;   for (int r = 0; r < 16; ++r) ps += p1[r];
;   { auto rr = __builtin_amdgcn_permlane32_swap(__float_as_uint(ps), __float_as_uint(ps), false, false);
;     ps = __uint_as_float(rr[0]) + __uint_as_float(rr[1]); }
;   l_reg = l_reg * alpha + ps;
; #pragma unroll
;   for (int g = 0; g < 4; ++g) {
;     int w = __builtin_amdgcn_cvt_pk_fp8_f32(p0[4 * g], p0[4 * g + 1], 0, false); p8[g] = __builtin_amdgcn_cvt_pk_fp8_f32(p0[4 * g + 2], p0[4 * g + 3], w, true);
;     int u = __builtin_amdgcn_cvt_pk_fp8_f32(p1[4 * g], p1[4 * g + 1], 0, false); p8[4 + g] = __builtin_amdgcn_cvt_pk_fp8_f32(p1[4 * g + 2], p1[4 * g + 3], u, true); }
; }
; __device__ __forceinline__ void pv8(f32x16* o, const char* Vt, const v8i32 p8, int r32, int hi) {
;   const int sw = (r32 >> 2) & 3, a0 = r32 * 64 + (((hi * 2) ^ sw) << 4), a1 = r32 * 64 + (((hi * 2 + 1) ^ sw) << 4);
; #pragma unroll
;   for (int d0 = 0; d0 < 4; ++d0) {
;     const v8i32 vf = cat8(*reinterpret_cast<const v4i32*>(Vt + d0 * 2048 + a0), *reinterpret_cast<const v4i32*>(Vt + d0 * 2048 + a1));
;     o[d0] = __builtin_amdgcn_mfma_scale_f32_32x32x64_f8f6f4(p8, vf, o[d0], 0, 0, 0, 127, 0, 127); }
; }
; __device__ __forceinline__ void qkt9(f32x16& p0, f32x16& p1, const char* Kn, const char* Kr, const v8i32* qf, const float init, int r32, int hi) {
; #pragma unroll
;   for (int r = 0; r < 16; ++r) { p0[r] = init; p1[r] = init; }
; #pragma unroll
;   for (int s = 0; s < 2; ++s) { const int c0 = s * 4 + hi * 2;
;     const v8i32 a0 = cat8(*reinterpret_cast<const v4i32*>(Kn + KN8SW(r32, c0)), *reinterpret_cast<const v4i32*>(Kn + KN8SW(r32, c0 + 1)));
;     const v8i32 a1 = cat8(*reinterpret_cast<const v4i32*>(Kn + 4096 + KN8SW(r32, c0)), *reinterpret_cast<const v4i32*>(Kn + 4096 + KN8SW(r32, c0 + 1)));
;     p0 = __builtin_amdgcn_mfma_scale_f32_32x32x64_f8f6f4(a0, qf[s], p0, 0, 0, 0, 127, 0, 124);
;     p1 = __builtin_amdgcn_mfma_scale_f32_32x32x64_f8f6f4(a1, qf[s], p1, 0, 0, 0, 127, 0, 124); }
;   { const int c0 = hi * 2;
.Lmla_h0_cont:
	ds_read_b128 v[82:85], v215 offset:51200
	ds_read_b128 v[86:89], v216 offset:51200
	ds_read_b128 v[222:225], v215 offset:55296
	ds_read_b128 v[226:229], v216 offset:55296
	s_add_i32 m0, s98, 0x0
	s_nop 0
	global_load_lds_dwordx4 v176, s[18:19]
	s_add_i32 m0, s98, 0x4000
	s_nop 0
	global_load_lds_dwordx4 v178, s[16:17]
	s_add_i32 m0, s98, 0x8000
	s_nop 0
	global_load_lds_dwordx4 v[180:181], off
	s_waitcnt lgkmcnt(2)
	v_mfma_scale_f32_32x32x64_f8f6f4 v[82:97], v[82:89], v[146:153], v[230:245], v194, v193 op_sel_hi:[0,0,0]
	v_exp_f32_e32 v0, v114
	v_exp_f32_e32 v177, v115
	v_exp_f32_e32 v179, v116
	v_exp_f32_e32 v254, v117
	v_add_f32_e32 v219, v0, v177
	v_cvt_pk_fp8_f32 v246, v0, v177
	v_add_f32_e32 v219, v179, v219
	v_add_f32_e32 v219, v254, v219
	v_cvt_pk_fp8_f32 v246, v179, v254 op_sel:[0,0,1]
	v_exp_f32_e32 v0, v118
	v_exp_f32_e32 v177, v119
	v_exp_f32_e32 v179, v120
	v_exp_f32_e32 v254, v121
	v_add_f32_e32 v219, v0, v219
	v_add_f32_e32 v219, v177, v219
	v_cvt_pk_fp8_f32 v247, v0, v177
	v_add_f32_e32 v219, v179, v219
	v_add_f32_e32 v219, v254, v219
	v_cvt_pk_fp8_f32 v247, v179, v254 op_sel:[0,0,1]
	ds_read_b128 v[114:117], v213 offset:51200
	ds_read_b128 v[118:121], v214 offset:51200
	s_waitcnt lgkmcnt(2)
	v_mfma_scale_f32_32x32x64_f8f6f4 v[66:81], v[222:229], v[146:153], v[230:245], v194, v193 op_sel_hi:[0,0,0]
	ds_read_b128 v[222:225], v213 offset:55296
	ds_read_b128 v[226:229], v214 offset:55296
	v_exp_f32_e32 v0, v122
	v_exp_f32_e32 v177, v123
	v_exp_f32_e32 v179, v124
	v_exp_f32_e32 v254, v125
	v_add_f32_e32 v219, v0, v219
	v_add_f32_e32 v219, v177, v219
	v_cvt_pk_fp8_f32 v248, v0, v177
	v_add_f32_e32 v219, v179, v219
	v_add_f32_e32 v219, v254, v219
	v_cvt_pk_fp8_f32 v248, v179, v254 op_sel:[0,0,1]
	v_exp_f32_e32 v0, v126
	v_exp_f32_e32 v177, v127
	v_exp_f32_e32 v179, v128
	v_exp_f32_e32 v254, v129
	v_add_f32_e32 v219, v0, v219
	v_add_f32_e32 v219, v177, v219
	v_cvt_pk_fp8_f32 v249, v0, v177
	v_add_f32_e32 v219, v179, v219
	v_add_f32_e32 v219, v254, v219
	v_cvt_pk_fp8_f32 v249, v179, v254 op_sel:[0,0,1]
	ds_read_b128 v[122:125], v185 offset:59392
	ds_read_b128 v[126:129], v186 offset:59392
	s_waitcnt lgkmcnt(4)
	v_mfma_scale_f32_32x32x64_f8f6f4 v[82:97], v[114:121], v[138:145], v[82:97], v194, v193 op_sel_hi:[0,0,0]
	v_exp_f32_e32 v0, v98
	v_exp_f32_e32 v177, v99
	v_exp_f32_e32 v179, v100
	v_exp_f32_e32 v254, v101
	v_add_f32_e32 v219, v0, v219
	v_add_f32_e32 v219, v177, v219
	v_cvt_pk_fp8_f32 v250, v0, v177
	v_add_f32_e32 v219, v179, v219
	v_add_f32_e32 v219, v254, v219
	v_cvt_pk_fp8_f32 v250, v179, v254 op_sel:[0,0,1]
	s_waitcnt lgkmcnt(2)
	v_mfma_scale_f32_32x32x64_f8f6f4 v[66:81], v[222:229], v[138:145], v[66:81], v194, v193 op_sel_hi:[0,0,0]
	ds_read_b128 v[222:225], v185 offset:61440
	ds_read_b128 v[226:229], v186 offset:61440
	v_exp_f32_e32 v0, v102
	v_exp_f32_e32 v177, v103
	v_exp_f32_e32 v179, v104
	v_exp_f32_e32 v254, v105
	v_add_f32_e32 v219, v0, v219
	v_add_f32_e32 v219, v177, v219
	v_cvt_pk_fp8_f32 v251, v0, v177
	v_add_f32_e32 v219, v179, v219
	v_add_f32_e32 v219, v254, v219
	v_cvt_pk_fp8_f32 v251, v179, v254 op_sel:[0,0,1]
	v_exp_f32_e32 v0, v106
	v_exp_f32_e32 v177, v107
	v_exp_f32_e32 v179, v108
	v_exp_f32_e32 v254, v109
	v_add_f32_e32 v219, v0, v219
	v_add_f32_e32 v219, v177, v219
	v_cvt_pk_fp8_f32 v252, v0, v177
	v_add_f32_e32 v219, v179, v219
	v_add_f32_e32 v219, v254, v219
	v_cvt_pk_fp8_f32 v252, v179, v254 op_sel:[0,0,1]
	s_waitcnt lgkmcnt(2)
	v_mfma_scale_f32_32x32x64_f8f6f4 v[82:97], v[122:129], v[130:137], v[82:97], v194, v193 op_sel_hi:[0,0,0]
	v_exp_f32_e32 v0, v110
	v_exp_f32_e32 v177, v111
	v_exp_f32_e32 v179, v112
	v_exp_f32_e32 v254, v113
	v_add_f32_e32 v219, v0, v219
	v_add_f32_e32 v219, v177, v219
	v_cvt_pk_fp8_f32 v253, v0, v177
	v_add_f32_e32 v219, v179, v219
	v_add_f32_e32 v219, v254, v219
	v_cvt_pk_fp8_f32 v253, v179, v254 op_sel:[0,0,1]
	ds_read_b128 v[122:125], v185 offset:8192
	ds_read_b128 v[126:129], v186 offset:8192
	ds_read_b128 v[114:117], v185 offset:10240
	ds_read_b128 v[118:121], v186 offset:10240
	ds_read_b128 v[106:109], v185 offset:12288
	ds_read_b128 v[110:113], v186 offset:12288
	ds_read_b128 v[98:101], v185 offset:14336
	ds_read_b128 v[102:105], v186 offset:14336
	s_waitcnt lgkmcnt(8)
	v_mfma_scale_f32_32x32x64_f8f6f4 v[66:81], v[222:229], v[130:137], v[66:81], v194, v193 op_sel_hi:[0,0,0]
	v_mov_b32_e32 v0, v219
	s_nop 1
	v_permlane32_swap_b32_e32 v219, v0
	v_add_f32_e32 v219, v219, v0
	v_fma_f32 v209, v209, v221, v219
	v_add_u32_e32 v176, 0x2000, v176
	v_add_u32_e32 v178, 0x20000, v178
	s_mov_b64 s[20:21], 0x1000
	v_lshl_add_u64 v[180:181], v[180:181], 0, s[20:21]
	v_max_f32_e32 v177, v82, v83
	v_max3_f32 v177, v177, v84, v85
	v_max3_f32 v177, v177, v86, v87
	v_max3_f32 v177, v177, v88, v89
	v_max3_f32 v177, v177, v90, v91
	v_max3_f32 v177, v177, v92, v93
	v_max3_f32 v177, v177, v94, v95
	v_max3_f32 v177, v177, v96, v97
	s_waitcnt lgkmcnt(6)
	v_mfma_scale_f32_32x32x64_f8f6f4 v[50:65], v[246:253], v[122:129], v[50:65], v194, v194 op_sel_hi:[0,0,0]
	v_max_f32_e32 v0, v66, v67
	v_max3_f32 v0, v0, v68, v69
	v_max3_f32 v0, v0, v70, v71
	s_waitcnt lgkmcnt(4)
	v_mfma_scale_f32_32x32x64_f8f6f4 v[34:49], v[246:253], v[114:121], v[34:49], v194, v194 op_sel_hi:[0,0,0]
	v_max3_f32 v0, v0, v72, v73
	v_max3_f32 v0, v0, v74, v75
	v_max3_f32 v0, v0, v76, v77
	s_waitcnt lgkmcnt(2)
	v_mfma_scale_f32_32x32x64_f8f6f4 v[18:33], v[246:253], v[106:113], v[18:33], v194, v194 op_sel_hi:[0,0,0]
	v_max3_f32 v0, v0, v78, v79
	v_max3_f32 v0, v0, v80, v81
	v_max_f32_e32 v177, v177, v0
	v_mov_b32_e32 v0, v177
	v_mov_b32_e32 v218, 1.0
	s_waitcnt lgkmcnt(0)
	v_mfma_scale_f32_32x32x64_f8f6f4 v[2:17], v[246:253], v[98:105], v[2:17], v194, v194 op_sel_hi:[0,0,0]
	s_waitcnt vmcnt(0)
	s_waitcnt lgkmcnt(0)
	s_barrier
	v_permlane32_swap_b32_e32 v177, v0
	v_max_f32_e32 v177, v177, v0
	v_cmp_ge_f32_e32 vcc, s90, v177
	s_cmp_eq_u64 vcc, exec
	s_cbranch_scc0 .Lmla_h1_newmax
; __device__ __forceinline__ void finishSM9(f32x16& p0, f32x16& p1, float alpha, float& l_reg, v8i32& p8) {
; #pragma unroll
;   for (int r = 0; r < 16; ++r) { p0[r] = __builtin_amdgcn_exp2f(p0[r]); p1[r] = __builtin_amdgcn_exp2f(p1[r]); }
;   float ps = 0;
; #pragma unroll
;   for (int r = 0; r < 16; ++r) ps += p0[r];
; #pragma unroll
;   for (int r = 0; r < 16; ++r) ps += p1[r];
;   { auto rr = __builtin_amdgcn_permlane32_swap(__float_as_uint(ps), __float_as_uint(ps), false, false);
;     ps = __uint_as_float(rr[0]) + __uint_as_float(rr[1]); }
;   l_reg = l_reg * alpha + ps;
; #pragma unroll
;   for (int g = 0; g < 4; ++g) {
;     int w = __builtin_amdgcn_cvt_pk_fp8_f32(p0[4 * g], p0[4 * g + 1], 0, false); p8[g] = __builtin_amdgcn_cvt_pk_fp8_f32(p0[4 * g + 2], p0[4 * g + 3], w, true);
;     int u = __builtin_amdgcn_cvt_pk_fp8_f32(p1[4 * g], p1[4 * g + 1], 0, false); p8[4 + g] = __builtin_amdgcn_cvt_pk_fp8_f32(p1[4 * g + 2], p1[4 * g + 3], u, true); }
; }
; __device__ __forceinline__ void pv8(f32x16* o, const char* Vt, const v8i32 p8, int r32, int hi) {
;   const int sw = (r32 >> 2) & 3, a0 = r32 * 64 + (((hi * 2) ^ sw) << 4), a1 = r32 * 64 + (((hi * 2 + 1) ^ sw) << 4);
; #pragma unroll
;   for (int d0 = 0; d0 < 4; ++d0) {
;     const v8i32 vf = cat8(*reinterpret_cast<const v4i32*>(Vt + d0 * 2048 + a0), *reinterpret_cast<const v4i32*>(Vt + d0 * 2048 + a1));
;     o[d0] = __builtin_amdgcn_mfma_scale_f32_32x32x64_f8f6f4(p8, vf, o[d0], 0, 0, 0, 127, 0, 127); }
; }
; __device__ __forceinline__ void qkt9(f32x16& p0, f32x16& p1, const char* Kn, const char* Kr, const v8i32* qf, const float init, int r32, int hi) {
; #pragma unroll
;   for (int r = 0; r < 16; ++r) { p0[r] = init; p1[r] = init; }
; #pragma unroll
;   for (int s = 0; s < 2; ++s) { const int c0 = s * 4 + hi * 2;
;     const v8i32 a0 = cat8(*reinterpret_cast<const v4i32*>(Kn + KN8SW(r32, c0)), *reinterpret_cast<const v4i32*>(Kn + KN8SW(r32, c0 + 1)));
;     const v8i32 a1 = cat8(*reinterpret_cast<const v4i32*>(Kn + 4096 + KN8SW(r32, c0)), *reinterpret_cast<const v4i32*>(Kn + 4096 + KN8SW(r32, c0 + 1)));
;     p0 = __builtin_amdgcn_mfma_scale_f32_32x32x64_f8f6f4(a0, qf[s], p0, 0, 0, 0, 127, 0, 124);
;     p1 = __builtin_amdgcn_mfma_scale_f32_32x32x64_f8f6f4(a1, qf[s], p1, 0, 0, 0, 127, 0, 124); }
;   { const int c0 = hi * 2;
.Lmla_h1_cont:
	ds_read_b128 v[114:117], v215 offset:16384
	ds_read_b128 v[118:121], v216 offset:16384
	ds_read_b128 v[222:225], v215 offset:20480
	ds_read_b128 v[226:229], v216 offset:20480
	s_add_i32 m0, s98, 0x2000
	s_nop 0
	global_load_lds_dwordx4 v176, s[18:19]
	s_add_i32 m0, s98, 0x6000
	s_nop 0
	global_load_lds_dwordx4 v178, s[16:17]
	s_add_i32 m0, s98, 0x9000
	s_nop 0
	global_load_lds_dwordx4 v[180:181], off
	s_waitcnt lgkmcnt(2)
	v_mfma_scale_f32_32x32x64_f8f6f4 v[114:129], v[114:121], v[146:153], v[230:245], v194, v193 op_sel_hi:[0,0,0]
	v_exp_f32_e32 v0, v82
	v_exp_f32_e32 v177, v83
	v_exp_f32_e32 v179, v84
	v_exp_f32_e32 v254, v85
	v_add_f32_e32 v219, v0, v177
	v_cvt_pk_fp8_f32 v246, v0, v177
	v_add_f32_e32 v219, v179, v219
	v_add_f32_e32 v219, v254, v219
	v_cvt_pk_fp8_f32 v246, v179, v254 op_sel:[0,0,1]
	v_exp_f32_e32 v0, v86
	v_exp_f32_e32 v177, v87
	v_exp_f32_e32 v179, v88
	v_exp_f32_e32 v254, v89
	v_add_f32_e32 v219, v0, v219
	v_add_f32_e32 v219, v177, v219
	v_cvt_pk_fp8_f32 v247, v0, v177
	v_add_f32_e32 v219, v179, v219
	v_add_f32_e32 v219, v254, v219
	v_cvt_pk_fp8_f32 v247, v179, v254 op_sel:[0,0,1]
	ds_read_b128 v[82:85], v213 offset:16384
	ds_read_b128 v[86:89], v214 offset:16384
	s_waitcnt lgkmcnt(2)
	v_mfma_scale_f32_32x32x64_f8f6f4 v[98:113], v[222:229], v[146:153], v[230:245], v194, v193 op_sel_hi:[0,0,0]
	ds_read_b128 v[222:225], v213 offset:20480
	ds_read_b128 v[226:229], v214 offset:20480
	v_exp_f32_e32 v0, v90
	v_exp_f32_e32 v177, v91
	v_exp_f32_e32 v179, v92
	v_exp_f32_e32 v254, v93
	v_add_f32_e32 v219, v0, v219
	v_add_f32_e32 v219, v177, v219
	v_cvt_pk_fp8_f32 v248, v0, v177
	v_add_f32_e32 v219, v179, v219
	v_add_f32_e32 v219, v254, v219
	v_cvt_pk_fp8_f32 v248, v179, v254 op_sel:[0,0,1]
	v_exp_f32_e32 v0, v94
	v_exp_f32_e32 v177, v95
	v_exp_f32_e32 v179, v96
	v_exp_f32_e32 v254, v97
	v_add_f32_e32 v219, v0, v219
	v_add_f32_e32 v219, v177, v219
	v_cvt_pk_fp8_f32 v249, v0, v177
	v_add_f32_e32 v219, v179, v219
	v_add_f32_e32 v219, v254, v219
	v_cvt_pk_fp8_f32 v249, v179, v254 op_sel:[0,0,1]
	ds_read_b128 v[90:93], v185 offset:32768
	ds_read_b128 v[94:97], v186 offset:32768
	s_waitcnt lgkmcnt(4)
	v_mfma_scale_f32_32x32x64_f8f6f4 v[114:129], v[82:89], v[138:145], v[114:129], v194, v193 op_sel_hi:[0,0,0]
	v_exp_f32_e32 v0, v66
	v_exp_f32_e32 v177, v67
	v_exp_f32_e32 v179, v68
	v_exp_f32_e32 v254, v69
	v_add_f32_e32 v219, v0, v219
	v_add_f32_e32 v219, v177, v219
	v_cvt_pk_fp8_f32 v250, v0, v177
	v_add_f32_e32 v219, v179, v219
	v_add_f32_e32 v219, v254, v219
	v_cvt_pk_fp8_f32 v250, v179, v254 op_sel:[0,0,1]
	s_waitcnt lgkmcnt(2)
	v_mfma_scale_f32_32x32x64_f8f6f4 v[98:113], v[222:229], v[138:145], v[98:113], v194, v193 op_sel_hi:[0,0,0]
	ds_read_b128 v[222:225], v185 offset:34816
	ds_read_b128 v[226:229], v186 offset:34816
	v_exp_f32_e32 v0, v70
	v_exp_f32_e32 v177, v71
	v_exp_f32_e32 v179, v72
	v_exp_f32_e32 v254, v73
	v_add_f32_e32 v219, v0, v219
	v_add_f32_e32 v219, v177, v219
	v_cvt_pk_fp8_f32 v251, v0, v177
	v_add_f32_e32 v219, v179, v219
	v_add_f32_e32 v219, v254, v219
	v_cvt_pk_fp8_f32 v251, v179, v254 op_sel:[0,0,1]
	v_exp_f32_e32 v0, v74
	v_exp_f32_e32 v177, v75
	v_exp_f32_e32 v179, v76
	v_exp_f32_e32 v254, v77
	v_add_f32_e32 v219, v0, v219
	v_add_f32_e32 v219, v177, v219
	v_cvt_pk_fp8_f32 v252, v0, v177
	v_add_f32_e32 v219, v179, v219
	v_add_f32_e32 v219, v254, v219
	v_cvt_pk_fp8_f32 v252, v179, v254 op_sel:[0,0,1]
	s_waitcnt lgkmcnt(2)
	v_mfma_scale_f32_32x32x64_f8f6f4 v[114:129], v[90:97], v[130:137], v[114:129], v194, v193 op_sel_hi:[0,0,0]
	v_exp_f32_e32 v0, v78
	v_exp_f32_e32 v177, v79
	v_exp_f32_e32 v179, v80
	v_exp_f32_e32 v254, v81
	v_add_f32_e32 v219, v0, v219
	v_add_f32_e32 v219, v177, v219
	v_cvt_pk_fp8_f32 v253, v0, v177
	v_add_f32_e32 v219, v179, v219
	v_add_f32_e32 v219, v254, v219
	v_cvt_pk_fp8_f32 v253, v179, v254 op_sel:[0,0,1]
	ds_read_b128 v[90:93], v185 offset:43008
	ds_read_b128 v[94:97], v186 offset:43008
	ds_read_b128 v[82:85], v185 offset:45056
	ds_read_b128 v[86:89], v186 offset:45056
	ds_read_b128 v[74:77], v185 offset:47104
	ds_read_b128 v[78:81], v186 offset:47104
	ds_read_b128 v[66:69], v185 offset:49152
	ds_read_b128 v[70:73], v186 offset:49152
	s_waitcnt lgkmcnt(8)
	v_mfma_scale_f32_32x32x64_f8f6f4 v[98:113], v[222:229], v[130:137], v[98:113], v194, v193 op_sel_hi:[0,0,0]
	v_mov_b32_e32 v0, v219
	s_nop 1
	v_permlane32_swap_b32_e32 v219, v0
	v_add_f32_e32 v219, v219, v0
	v_fma_f32 v209, v209, v218, v219
	v_add_u32_e32 v176, 0x2000, v176
	v_add_u32_e32 v178, 0x20000, v178
	s_mov_b64 s[20:21], 0x1000
	v_lshl_add_u64 v[180:181], v[180:181], 0, s[20:21]
	v_max_f32_e32 v177, v114, v115
	v_max3_f32 v177, v177, v116, v117
	v_max3_f32 v177, v177, v118, v119
	v_max3_f32 v177, v177, v120, v121
	v_max3_f32 v177, v177, v122, v123
	v_max3_f32 v177, v177, v124, v125
	v_max3_f32 v177, v177, v126, v127
	v_max3_f32 v177, v177, v128, v129
	s_waitcnt lgkmcnt(6)
	v_mfma_scale_f32_32x32x64_f8f6f4 v[50:65], v[246:253], v[90:97], v[50:65], v194, v194 op_sel_hi:[0,0,0]
	v_max_f32_e32 v0, v98, v99
	v_max3_f32 v0, v0, v100, v101
	v_max3_f32 v0, v0, v102, v103
	s_waitcnt lgkmcnt(4)
	v_mfma_scale_f32_32x32x64_f8f6f4 v[34:49], v[246:253], v[82:89], v[34:49], v194, v194 op_sel_hi:[0,0,0]
	v_max3_f32 v0, v0, v104, v105
	v_max3_f32 v0, v0, v106, v107
	v_max3_f32 v0, v0, v108, v109
	s_waitcnt lgkmcnt(2)
	v_mfma_scale_f32_32x32x64_f8f6f4 v[18:33], v[246:253], v[74:81], v[18:33], v194, v194 op_sel_hi:[0,0,0]
	v_max3_f32 v0, v0, v110, v111
	v_max3_f32 v0, v0, v112, v113
	v_max_f32_e32 v177, v177, v0
	v_mov_b32_e32 v0, v177
	v_mov_b32_e32 v221, 1.0
	s_waitcnt lgkmcnt(0)
	v_mfma_scale_f32_32x32x64_f8f6f4 v[2:17], v[246:253], v[66:73], v[2:17], v194, v194 op_sel_hi:[0,0,0]
	s_waitcnt vmcnt(0)
	s_waitcnt lgkmcnt(0)
	s_barrier
	v_permlane32_swap_b32_e32 v177, v0
	v_max_f32_e32 v177, v177, v0
	v_cmp_ge_f32_e32 vcc, s90, v177
	s_cmp_eq_u64 vcc, exec
	s_cbranch_scc0 .Lmla_h2_newmax
; __device__ __forceinline__ void finishSM9(f32x16& p0, f32x16& p1, float alpha, float& l_reg, v8i32& p8) {
; #pragma unroll
;   for (int r = 0; r < 16; ++r) { p0[r] = __builtin_amdgcn_exp2f(p0[r]); p1[r] = __builtin_amdgcn_exp2f(p1[r]); }
;   float ps = 0;
; #pragma unroll
;   for (int r = 0; r < 16; ++r) ps += p0[r];
; #pragma unroll
;   for (int r = 0; r < 16; ++r) ps += p1[r];
;   { auto rr = __builtin_amdgcn_permlane32_swap(__float_as_uint(ps), __float_as_uint(ps), false, false);
;     ps = __uint_as_float(rr[0]) + __uint_as_float(rr[1]); }
;   l_reg = l_reg * alpha + ps;
; #pragma unroll
;   for (int g = 0; g < 4; ++g) {
;     int w = __builtin_amdgcn_cvt_pk_fp8_f32(p0[4 * g], p0[4 * g + 1], 0, false); p8[g] = __builtin_amdgcn_cvt_pk_fp8_f32(p0[4 * g + 2], p0[4 * g + 3], w, true);
;     int u = __builtin_amdgcn_cvt_pk_fp8_f32(p1[4 * g], p1[4 * g + 1], 0, false); p8[4 + g] = __builtin_amdgcn_cvt_pk_fp8_f32(p1[4 * g + 2], p1[4 * g + 3], u, true); }
; }
; __device__ __forceinline__ void pv8(f32x16* o, const char* Vt, const v8i32 p8, int r32, int hi) {
;   const int sw = (r32 >> 2) & 3, a0 = r32 * 64 + (((hi * 2) ^ sw) << 4), a1 = r32 * 64 + (((hi * 2 + 1) ^ sw) << 4);
; #pragma unroll
;   for (int d0 = 0; d0 < 4; ++d0) {
;     const v8i32 vf = cat8(*reinterpret_cast<const v4i32*>(Vt + d0 * 2048 + a0), *reinterpret_cast<const v4i32*>(Vt + d0 * 2048 + a1));
;     o[d0] = __builtin_amdgcn_mfma_scale_f32_32x32x64_f8f6f4(p8, vf, o[d0], 0, 0, 0, 127, 0, 127); }
; }
; __device__ __forceinline__ void qkt9(f32x16& p0, f32x16& p1, const char* Kn, const char* Kr, const v8i32* qf, const float init, int r32, int hi) {
; #pragma unroll
;   for (int r = 0; r < 16; ++r) { p0[r] = init; p1[r] = init; }
; #pragma unroll
;   for (int s = 0; s < 2; ++s) { const int c0 = s * 4 + hi * 2;
;     const v8i32 a0 = cat8(*reinterpret_cast<const v4i32*>(Kn + KN8SW(r32, c0)), *reinterpret_cast<const v4i32*>(Kn + KN8SW(r32, c0 + 1)));
;     const v8i32 a1 = cat8(*reinterpret_cast<const v4i32*>(Kn + 4096 + KN8SW(r32, c0)), *reinterpret_cast<const v4i32*>(Kn + 4096 + KN8SW(r32, c0 + 1)));
;     p0 = __builtin_amdgcn_mfma_scale_f32_32x32x64_f8f6f4(a0, qf[s], p0, 0, 0, 0, 127, 0, 124);
;     p1 = __builtin_amdgcn_mfma_scale_f32_32x32x64_f8f6f4(a1, qf[s], p1, 0, 0, 0, 127, 0, 124); }
;   { const int c0 = hi * 2;
.Lmla_h2_cont:
	ds_read_b128 v[82:85], v215 offset:24576
	ds_read_b128 v[86:89], v216 offset:24576
	ds_read_b128 v[222:225], v215 offset:28672
	ds_read_b128 v[226:229], v216 offset:28672
	s_add_i32 m0, s98, 0xa800
	s_nop 0
	global_load_lds_dwordx4 v176, s[18:19]
	s_add_i32 m0, s98, 0xc800
	s_nop 0
	global_load_lds_dwordx4 v178, s[16:17]
	s_add_i32 m0, s98, 0xe800
	s_nop 0
	global_load_lds_dwordx4 v[180:181], off
	s_waitcnt lgkmcnt(2)
	v_mfma_scale_f32_32x32x64_f8f6f4 v[82:97], v[82:89], v[146:153], v[230:245], v194, v193 op_sel_hi:[0,0,0]
	v_exp_f32_e32 v0, v114
	v_exp_f32_e32 v177, v115
	v_exp_f32_e32 v179, v116
	v_exp_f32_e32 v254, v117
	v_add_f32_e32 v219, v0, v177
	v_cvt_pk_fp8_f32 v246, v0, v177
	v_add_f32_e32 v219, v179, v219
	v_add_f32_e32 v219, v254, v219
	v_cvt_pk_fp8_f32 v246, v179, v254 op_sel:[0,0,1]
	v_exp_f32_e32 v0, v118
	v_exp_f32_e32 v177, v119
	v_exp_f32_e32 v179, v120
	v_exp_f32_e32 v254, v121
	v_add_f32_e32 v219, v0, v219
	v_add_f32_e32 v219, v177, v219
	v_cvt_pk_fp8_f32 v247, v0, v177
	v_add_f32_e32 v219, v179, v219
	v_add_f32_e32 v219, v254, v219
	v_cvt_pk_fp8_f32 v247, v179, v254 op_sel:[0,0,1]
	ds_read_b128 v[114:117], v213 offset:24576
	ds_read_b128 v[118:121], v214 offset:24576
	s_waitcnt lgkmcnt(2)
	v_mfma_scale_f32_32x32x64_f8f6f4 v[66:81], v[222:229], v[146:153], v[230:245], v194, v193 op_sel_hi:[0,0,0]
	ds_read_b128 v[222:225], v213 offset:28672
	ds_read_b128 v[226:229], v214 offset:28672
	v_exp_f32_e32 v0, v122
	v_exp_f32_e32 v177, v123
	v_exp_f32_e32 v179, v124
	v_exp_f32_e32 v254, v125
	v_add_f32_e32 v219, v0, v219
	v_add_f32_e32 v219, v177, v219
	v_cvt_pk_fp8_f32 v248, v0, v177
	v_add_f32_e32 v219, v179, v219
	v_add_f32_e32 v219, v254, v219
	v_cvt_pk_fp8_f32 v248, v179, v254 op_sel:[0,0,1]
	v_exp_f32_e32 v0, v126
	v_exp_f32_e32 v177, v127
	v_exp_f32_e32 v179, v128
	v_exp_f32_e32 v254, v129
	v_add_f32_e32 v219, v0, v219
	v_add_f32_e32 v219, v177, v219
	v_cvt_pk_fp8_f32 v249, v0, v177
	v_add_f32_e32 v219, v179, v219
	v_add_f32_e32 v219, v254, v219
	v_cvt_pk_fp8_f32 v249, v179, v254 op_sel:[0,0,1]
	ds_read_b128 v[122:125], v185 offset:36864
	ds_read_b128 v[126:129], v186 offset:36864
	s_waitcnt lgkmcnt(4)
	v_mfma_scale_f32_32x32x64_f8f6f4 v[82:97], v[114:121], v[138:145], v[82:97], v194, v193 op_sel_hi:[0,0,0]
	v_exp_f32_e32 v0, v98
	v_exp_f32_e32 v177, v99
	v_exp_f32_e32 v179, v100
	v_exp_f32_e32 v254, v101
	v_add_f32_e32 v219, v0, v219
	v_add_f32_e32 v219, v177, v219
	v_cvt_pk_fp8_f32 v250, v0, v177
	v_add_f32_e32 v219, v179, v219
	v_add_f32_e32 v219, v254, v219
	v_cvt_pk_fp8_f32 v250, v179, v254 op_sel:[0,0,1]
	s_waitcnt lgkmcnt(2)
	v_mfma_scale_f32_32x32x64_f8f6f4 v[66:81], v[222:229], v[138:145], v[66:81], v194, v193 op_sel_hi:[0,0,0]
	ds_read_b128 v[222:225], v185 offset:38912
	ds_read_b128 v[226:229], v186 offset:38912
	v_exp_f32_e32 v0, v102
	v_exp_f32_e32 v177, v103
	v_exp_f32_e32 v179, v104
	v_exp_f32_e32 v254, v105
	v_add_f32_e32 v219, v0, v219
	v_add_f32_e32 v219, v177, v219
	v_cvt_pk_fp8_f32 v251, v0, v177
	v_add_f32_e32 v219, v179, v219
	v_add_f32_e32 v219, v254, v219
	v_cvt_pk_fp8_f32 v251, v179, v254 op_sel:[0,0,1]
	v_exp_f32_e32 v0, v106
	v_exp_f32_e32 v177, v107
	v_exp_f32_e32 v179, v108
	v_exp_f32_e32 v254, v109
	v_add_f32_e32 v219, v0, v219
	v_add_f32_e32 v219, v177, v219
	v_cvt_pk_fp8_f32 v252, v0, v177
	v_add_f32_e32 v219, v179, v219
	v_add_f32_e32 v219, v254, v219
	v_cvt_pk_fp8_f32 v252, v179, v254 op_sel:[0,0,1]
	s_waitcnt lgkmcnt(2)
	v_mfma_scale_f32_32x32x64_f8f6f4 v[82:97], v[122:129], v[130:137], v[82:97], v194, v193 op_sel_hi:[0,0,0]
	v_exp_f32_e32 v0, v110
	v_exp_f32_e32 v177, v111
	v_exp_f32_e32 v179, v112
	v_exp_f32_e32 v254, v113
	v_add_f32_e32 v219, v0, v219
	v_add_f32_e32 v219, v177, v219
	v_cvt_pk_fp8_f32 v253, v0, v177
	v_add_f32_e32 v219, v179, v219
	v_add_f32_e32 v219, v254, v219
	v_cvt_pk_fp8_f32 v253, v179, v254 op_sel:[0,0,1]
	ds_read_b128 v[122:125], v185 offset:0
	ds_read_b128 v[126:129], v186 offset:0
	ds_read_b128 v[114:117], v185 offset:2048
	ds_read_b128 v[118:121], v186 offset:2048
	ds_read_b128 v[106:109], v185 offset:4096
	ds_read_b128 v[110:113], v186 offset:4096
	ds_read_b128 v[98:101], v185 offset:6144
	ds_read_b128 v[102:105], v186 offset:6144
	s_waitcnt lgkmcnt(8)
	v_mfma_scale_f32_32x32x64_f8f6f4 v[66:81], v[222:229], v[130:137], v[66:81], v194, v193 op_sel_hi:[0,0,0]
	v_mov_b32_e32 v0, v219
	s_nop 1
	v_permlane32_swap_b32_e32 v219, v0
	v_add_f32_e32 v219, v219, v0
	v_fma_f32 v209, v209, v221, v219
	v_add_u32_e32 v176, 0x2000, v176
	v_add_u32_e32 v178, 0x20000, v178
	s_mov_b64 s[20:21], 0x1000
	v_lshl_add_u64 v[180:181], v[180:181], 0, s[20:21]
	v_max_f32_e32 v177, v82, v83
	v_max3_f32 v177, v177, v84, v85
	v_max3_f32 v177, v177, v86, v87
	v_max3_f32 v177, v177, v88, v89
	v_max3_f32 v177, v177, v90, v91
	v_max3_f32 v177, v177, v92, v93
	v_max3_f32 v177, v177, v94, v95
	v_max3_f32 v177, v177, v96, v97
	s_waitcnt lgkmcnt(6)
	v_mfma_scale_f32_32x32x64_f8f6f4 v[50:65], v[246:253], v[122:129], v[50:65], v194, v194 op_sel_hi:[0,0,0]
	v_max_f32_e32 v0, v66, v67
	v_max3_f32 v0, v0, v68, v69
	v_max3_f32 v0, v0, v70, v71
	s_waitcnt lgkmcnt(4)
	v_mfma_scale_f32_32x32x64_f8f6f4 v[34:49], v[246:253], v[114:121], v[34:49], v194, v194 op_sel_hi:[0,0,0]
	v_max3_f32 v0, v0, v72, v73
	v_max3_f32 v0, v0, v74, v75
	v_max3_f32 v0, v0, v76, v77
	s_waitcnt lgkmcnt(2)
	v_mfma_scale_f32_32x32x64_f8f6f4 v[18:33], v[246:253], v[106:113], v[18:33], v194, v194 op_sel_hi:[0,0,0]
	v_max3_f32 v0, v0, v78, v79
	v_max3_f32 v0, v0, v80, v81
	v_max_f32_e32 v177, v177, v0
	v_mov_b32_e32 v0, v177
	v_mov_b32_e32 v218, 1.0
	s_waitcnt lgkmcnt(0)
	v_mfma_scale_f32_32x32x64_f8f6f4 v[2:17], v[246:253], v[98:105], v[2:17], v194, v194 op_sel_hi:[0,0,0]
	s_waitcnt vmcnt(0)
	s_waitcnt lgkmcnt(0)
	s_barrier
	v_permlane32_swap_b32_e32 v177, v0
	v_max_f32_e32 v177, v177, v0
	v_cmp_ge_f32_e32 vcc, s90, v177
	s_cmp_eq_u64 vcc, exec
	s_cbranch_scc0 .Lmla_h3_newmax
; __device__ __forceinline__ void finishSM9(f32x16& p0, f32x16& p1, float alpha, float& l_reg, v8i32& p8) {
; #pragma unroll
;   for (int r = 0; r < 16; ++r) { p0[r] = __builtin_amdgcn_exp2f(p0[r]); p1[r] = __builtin_amdgcn_exp2f(p1[r]); }
;   float ps = 0;
; #pragma unroll
;   for (int r = 0; r < 16; ++r) ps += p0[r];
; #pragma unroll
;   for (int r = 0; r < 16; ++r) ps += p1[r];
;   { auto rr = __builtin_amdgcn_permlane32_swap(__float_as_uint(ps), __float_as_uint(ps), false, false);
;     ps = __uint_as_float(rr[0]) + __uint_as_float(rr[1]); }
;   l_reg = l_reg * alpha + ps;
; #pragma unroll
;   for (int g = 0; g < 4; ++g) {
;     int w = __builtin_amdgcn_cvt_pk_fp8_f32(p0[4 * g], p0[4 * g + 1], 0, false); p8[g] = __builtin_amdgcn_cvt_pk_fp8_f32(p0[4 * g + 2], p0[4 * g + 3], w, true);
;     int u = __builtin_amdgcn_cvt_pk_fp8_f32(p1[4 * g], p1[4 * g + 1], 0, false); p8[4 + g] = __builtin_amdgcn_cvt_pk_fp8_f32(p1[4 * g + 2], p1[4 * g + 3], u, true); }
; }
; __device__ __forceinline__ void pv8(f32x16* o, const char* Vt, const v8i32 p8, int r32, int hi) {
;   const int sw = (r32 >> 2) & 3, a0 = r32 * 64 + (((hi * 2) ^ sw) << 4), a1 = r32 * 64 + (((hi * 2 + 1) ^ sw) << 4);
; #pragma unroll
;   for (int d0 = 0; d0 < 4; ++d0) {
;     const v8i32 vf = cat8(*reinterpret_cast<const v4i32*>(Vt + d0 * 2048 + a0), *reinterpret_cast<const v4i32*>(Vt + d0 * 2048 + a1));
;     o[d0] = __builtin_amdgcn_mfma_scale_f32_32x32x64_f8f6f4(p8, vf, o[d0], 0, 0, 0, 127, 0, 127); }
; }
; __device__ __forceinline__ void qkt9(f32x16& p0, f32x16& p1, const char* Kn, const char* Kr, const v8i32* qf, const float init, int r32, int hi) {
; #pragma unroll
;   for (int r = 0; r < 16; ++r) { p0[r] = init; p1[r] = init; }
; #pragma unroll
;   for (int s = 0; s < 2; ++s) { const int c0 = s * 4 + hi * 2;
;     const v8i32 a0 = cat8(*reinterpret_cast<const v4i32*>(Kn + KN8SW(r32, c0)), *reinterpret_cast<const v4i32*>(Kn + KN8SW(r32, c0 + 1)));
;     const v8i32 a1 = cat8(*reinterpret_cast<const v4i32*>(Kn + 4096 + KN8SW(r32, c0)), *reinterpret_cast<const v4i32*>(Kn + 4096 + KN8SW(r32, c0 + 1)));
;     p0 = __builtin_amdgcn_mfma_scale_f32_32x32x64_f8f6f4(a0, qf[s], p0, 0, 0, 0, 127, 0, 124);
;     p1 = __builtin_amdgcn_mfma_scale_f32_32x32x64_f8f6f4(a1, qf[s], p1, 0, 0, 0, 127, 0, 124); }
;   { const int c0 = hi * 2;
.Lmla_h3_cont:
	ds_read_b128 v[114:117], v215 offset:51200
	ds_read_b128 v[118:121], v216 offset:51200
	ds_read_b128 v[222:225], v215 offset:55296
	ds_read_b128 v[226:229], v216 offset:55296
	s_add_i32 m0, s98, 0x0
	s_nop 0
	global_load_lds_dwordx4 v176, s[18:19]
	s_add_i32 m0, s98, 0x4000
	s_nop 0
	global_load_lds_dwordx4 v178, s[16:17]
	s_add_i32 m0, s98, 0x8000
	s_nop 0
	global_load_lds_dwordx4 v[180:181], off
	s_waitcnt lgkmcnt(2)
	v_mfma_scale_f32_32x32x64_f8f6f4 v[114:129], v[114:121], v[146:153], v[230:245], v194, v193 op_sel_hi:[0,0,0]
	v_exp_f32_e32 v0, v82
	v_exp_f32_e32 v177, v83
	v_exp_f32_e32 v179, v84
	v_exp_f32_e32 v254, v85
	v_add_f32_e32 v219, v0, v177
	v_cvt_pk_fp8_f32 v246, v0, v177
	v_add_f32_e32 v219, v179, v219
	v_add_f32_e32 v219, v254, v219
	v_cvt_pk_fp8_f32 v246, v179, v254 op_sel:[0,0,1]
	v_exp_f32_e32 v0, v86
	v_exp_f32_e32 v177, v87
	v_exp_f32_e32 v179, v88
	v_exp_f32_e32 v254, v89
	v_add_f32_e32 v219, v0, v219
	v_add_f32_e32 v219, v177, v219
	v_cvt_pk_fp8_f32 v247, v0, v177
	v_add_f32_e32 v219, v179, v219
	v_add_f32_e32 v219, v254, v219
	v_cvt_pk_fp8_f32 v247, v179, v254 op_sel:[0,0,1]
	ds_read_b128 v[82:85], v213 offset:51200
	ds_read_b128 v[86:89], v214 offset:51200
	s_waitcnt lgkmcnt(2)
	v_mfma_scale_f32_32x32x64_f8f6f4 v[98:113], v[222:229], v[146:153], v[230:245], v194, v193 op_sel_hi:[0,0,0]
	ds_read_b128 v[222:225], v213 offset:55296
	ds_read_b128 v[226:229], v214 offset:55296
	v_exp_f32_e32 v0, v90
	v_exp_f32_e32 v177, v91
	v_exp_f32_e32 v179, v92
	v_exp_f32_e32 v254, v93
	v_add_f32_e32 v219, v0, v219
	v_add_f32_e32 v219, v177, v219
	v_cvt_pk_fp8_f32 v248, v0, v177
	v_add_f32_e32 v219, v179, v219
	v_add_f32_e32 v219, v254, v219
	v_cvt_pk_fp8_f32 v248, v179, v254 op_sel:[0,0,1]
	v_exp_f32_e32 v0, v94
	v_exp_f32_e32 v177, v95
	v_exp_f32_e32 v179, v96
	v_exp_f32_e32 v254, v97
	v_add_f32_e32 v219, v0, v219
	v_add_f32_e32 v219, v177, v219
	v_cvt_pk_fp8_f32 v249, v0, v177
	v_add_f32_e32 v219, v179, v219
	v_add_f32_e32 v219, v254, v219
	v_cvt_pk_fp8_f32 v249, v179, v254 op_sel:[0,0,1]
	ds_read_b128 v[90:93], v185 offset:59392
	ds_read_b128 v[94:97], v186 offset:59392
	s_waitcnt lgkmcnt(4)
	v_mfma_scale_f32_32x32x64_f8f6f4 v[114:129], v[82:89], v[138:145], v[114:129], v194, v193 op_sel_hi:[0,0,0]
	v_exp_f32_e32 v0, v66
	v_exp_f32_e32 v177, v67
	v_exp_f32_e32 v179, v68
	v_exp_f32_e32 v254, v69
	v_add_f32_e32 v219, v0, v219
	v_add_f32_e32 v219, v177, v219
	v_cvt_pk_fp8_f32 v250, v0, v177
	v_add_f32_e32 v219, v179, v219
	v_add_f32_e32 v219, v254, v219
	v_cvt_pk_fp8_f32 v250, v179, v254 op_sel:[0,0,1]
	s_waitcnt lgkmcnt(2)
	v_mfma_scale_f32_32x32x64_f8f6f4 v[98:113], v[222:229], v[138:145], v[98:113], v194, v193 op_sel_hi:[0,0,0]
	ds_read_b128 v[222:225], v185 offset:61440
	ds_read_b128 v[226:229], v186 offset:61440
	v_exp_f32_e32 v0, v70
	v_exp_f32_e32 v177, v71
	v_exp_f32_e32 v179, v72
	v_exp_f32_e32 v254, v73
	v_add_f32_e32 v219, v0, v219
	v_add_f32_e32 v219, v177, v219
	v_cvt_pk_fp8_f32 v251, v0, v177
	v_add_f32_e32 v219, v179, v219
	v_add_f32_e32 v219, v254, v219
	v_cvt_pk_fp8_f32 v251, v179, v254 op_sel:[0,0,1]
	v_exp_f32_e32 v0, v74
	v_exp_f32_e32 v177, v75
	v_exp_f32_e32 v179, v76
	v_exp_f32_e32 v254, v77
	v_add_f32_e32 v219, v0, v219
	v_add_f32_e32 v219, v177, v219
	v_cvt_pk_fp8_f32 v252, v0, v177
	v_add_f32_e32 v219, v179, v219
	v_add_f32_e32 v219, v254, v219
	v_cvt_pk_fp8_f32 v252, v179, v254 op_sel:[0,0,1]
	s_waitcnt lgkmcnt(2)
	v_mfma_scale_f32_32x32x64_f8f6f4 v[114:129], v[90:97], v[130:137], v[114:129], v194, v193 op_sel_hi:[0,0,0]
	v_exp_f32_e32 v0, v78
	v_exp_f32_e32 v177, v79
	v_exp_f32_e32 v179, v80
	v_exp_f32_e32 v254, v81
	v_add_f32_e32 v219, v0, v219
	v_add_f32_e32 v219, v177, v219
	v_cvt_pk_fp8_f32 v253, v0, v177
	v_add_f32_e32 v219, v179, v219
	v_add_f32_e32 v219, v254, v219
	v_cvt_pk_fp8_f32 v253, v179, v254 op_sel:[0,0,1]
	ds_read_b128 v[90:93], v185 offset:8192
	ds_read_b128 v[94:97], v186 offset:8192
	ds_read_b128 v[82:85], v185 offset:10240
	ds_read_b128 v[86:89], v186 offset:10240
	ds_read_b128 v[74:77], v185 offset:12288
	ds_read_b128 v[78:81], v186 offset:12288
	ds_read_b128 v[66:69], v185 offset:14336
	ds_read_b128 v[70:73], v186 offset:14336
	s_waitcnt lgkmcnt(8)
	v_mfma_scale_f32_32x32x64_f8f6f4 v[98:113], v[222:229], v[130:137], v[98:113], v194, v193 op_sel_hi:[0,0,0]
	v_mov_b32_e32 v0, v219
	s_nop 1
	v_permlane32_swap_b32_e32 v219, v0
	v_add_f32_e32 v219, v219, v0
	v_fma_f32 v209, v209, v218, v219
	v_add_u32_e32 v176, 0x2000, v176
	v_add_u32_e32 v178, 0x20000, v178
	s_mov_b64 s[20:21], 0x1000
	v_lshl_add_u64 v[180:181], v[180:181], 0, s[20:21]
	v_max_f32_e32 v177, v114, v115
	v_max3_f32 v177, v177, v116, v117
	v_max3_f32 v177, v177, v118, v119
	v_max3_f32 v177, v177, v120, v121
	v_max3_f32 v177, v177, v122, v123
	v_max3_f32 v177, v177, v124, v125
	v_max3_f32 v177, v177, v126, v127
	v_max3_f32 v177, v177, v128, v129
	s_waitcnt lgkmcnt(6)
	v_mfma_scale_f32_32x32x64_f8f6f4 v[50:65], v[246:253], v[90:97], v[50:65], v194, v194 op_sel_hi:[0,0,0]
	v_max_f32_e32 v0, v98, v99
	v_max3_f32 v0, v0, v100, v101
	v_max3_f32 v0, v0, v102, v103
	s_waitcnt lgkmcnt(4)
	v_mfma_scale_f32_32x32x64_f8f6f4 v[34:49], v[246:253], v[82:89], v[34:49], v194, v194 op_sel_hi:[0,0,0]
	v_max3_f32 v0, v0, v104, v105
	v_max3_f32 v0, v0, v106, v107
	v_max3_f32 v0, v0, v108, v109
	s_waitcnt lgkmcnt(2)
	v_mfma_scale_f32_32x32x64_f8f6f4 v[18:33], v[246:253], v[74:81], v[18:33], v194, v194 op_sel_hi:[0,0,0]
	v_max3_f32 v0, v0, v110, v111
	v_max3_f32 v0, v0, v112, v113
	v_max_f32_e32 v177, v177, v0
	v_mov_b32_e32 v0, v177
	v_mov_b32_e32 v221, 1.0
	s_waitcnt lgkmcnt(0)
	v_mfma_scale_f32_32x32x64_f8f6f4 v[2:17], v[246:253], v[66:73], v[2:17], v194, v194 op_sel_hi:[0,0,0]
	s_waitcnt vmcnt(0)
	s_waitcnt lgkmcnt(0)
	s_barrier
	v_permlane32_swap_b32_e32 v177, v0
	v_max_f32_e32 v177, v177, v0
	v_cmp_ge_f32_e32 vcc, s90, v177
	s_cmp_eq_u64 vcc, exec
	s_cbranch_scc0 .Lmla_h4_newmax
; __device__ __forceinline__ void finishSM9(f32x16& p0, f32x16& p1, float alpha, float& l_reg, v8i32& p8) {
; #pragma unroll
;   for (int r = 0; r < 16; ++r) { p0[r] = __builtin_amdgcn_exp2f(p0[r]); p1[r] = __builtin_amdgcn_exp2f(p1[r]); }
;   float ps = 0;
; #pragma unroll
;   for (int r = 0; r < 16; ++r) ps += p0[r];
; #pragma unroll
;   for (int r = 0; r < 16; ++r) ps += p1[r];
;   { auto rr = __builtin_amdgcn_permlane32_swap(__float_as_uint(ps), __float_as_uint(ps), false, false);
;     ps = __uint_as_float(rr[0]) + __uint_as_float(rr[1]); }
;   l_reg = l_reg * alpha + ps;
; #pragma unroll
;   for (int g = 0; g < 4; ++g) {
;     int w = __builtin_amdgcn_cvt_pk_fp8_f32(p0[4 * g], p0[4 * g + 1], 0, false); p8[g] = __builtin_amdgcn_cvt_pk_fp8_f32(p0[4 * g + 2], p0[4 * g + 3], w, true);
;     int u = __builtin_amdgcn_cvt_pk_fp8_f32(p1[4 * g], p1[4 * g + 1], 0, false); p8[4 + g] = __builtin_amdgcn_cvt_pk_fp8_f32(p1[4 * g + 2], p1[4 * g + 3], u, true); }
; }
; __device__ __forceinline__ void pv8(f32x16* o, const char* Vt, const v8i32 p8, int r32, int hi) {
;   const int sw = (r32 >> 2) & 3, a0 = r32 * 64 + (((hi * 2) ^ sw) << 4), a1 = r32 * 64 + (((hi * 2 + 1) ^ sw) << 4);
; #pragma unroll
;   for (int d0 = 0; d0 < 4; ++d0) {
;     const v8i32 vf = cat8(*reinterpret_cast<const v4i32*>(Vt + d0 * 2048 + a0), *reinterpret_cast<const v4i32*>(Vt + d0 * 2048 + a1));
;     o[d0] = __builtin_amdgcn_mfma_scale_f32_32x32x64_f8f6f4(p8, vf, o[d0], 0, 0, 0, 127, 0, 127); }
; }
; __device__ __forceinline__ void qkt9(f32x16& p0, f32x16& p1, const char* Kn, const char* Kr, const v8i32* qf, const float init, int r32, int hi) {
; #pragma unroll
;   for (int r = 0; r < 16; ++r) { p0[r] = init; p1[r] = init; }
; #pragma unroll
;   for (int s = 0; s < 2; ++s) { const int c0 = s * 4 + hi * 2;
;     const v8i32 a0 = cat8(*reinterpret_cast<const v4i32*>(Kn + KN8SW(r32, c0)), *reinterpret_cast<const v4i32*>(Kn + KN8SW(r32, c0 + 1)));
;     const v8i32 a1 = cat8(*reinterpret_cast<const v4i32*>(Kn + 4096 + KN8SW(r32, c0)), *reinterpret_cast<const v4i32*>(Kn + 4096 + KN8SW(r32, c0 + 1)));
;     p0 = __builtin_amdgcn_mfma_scale_f32_32x32x64_f8f6f4(a0, qf[s], p0, 0, 0, 0, 127, 0, 124);
;     p1 = __builtin_amdgcn_mfma_scale_f32_32x32x64_f8f6f4(a1, qf[s], p1, 0, 0, 0, 127, 0, 124); }
;   { const int c0 = hi * 2;
.Lmla_h4_cont:
	ds_read_b128 v[82:85], v215 offset:16384
	ds_read_b128 v[86:89], v216 offset:16384
	ds_read_b128 v[222:225], v215 offset:20480
	ds_read_b128 v[226:229], v216 offset:20480
	s_add_i32 m0, s98, 0x2000
	s_nop 0
	global_load_lds_dwordx4 v176, s[18:19]
	s_add_i32 m0, s98, 0x6000
	s_nop 0
	global_load_lds_dwordx4 v178, s[16:17]
	s_add_i32 m0, s98, 0x9000
	s_nop 0
	global_load_lds_dwordx4 v[180:181], off
	s_waitcnt lgkmcnt(2)
	v_mfma_scale_f32_32x32x64_f8f6f4 v[82:97], v[82:89], v[146:153], v[230:245], v194, v193 op_sel_hi:[0,0,0]
	v_exp_f32_e32 v0, v114
	v_exp_f32_e32 v177, v115
	v_exp_f32_e32 v179, v116
	v_exp_f32_e32 v254, v117
	v_add_f32_e32 v219, v0, v177
	v_cvt_pk_fp8_f32 v246, v0, v177
	v_add_f32_e32 v219, v179, v219
	v_add_f32_e32 v219, v254, v219
	v_cvt_pk_fp8_f32 v246, v179, v254 op_sel:[0,0,1]
	v_exp_f32_e32 v0, v118
	v_exp_f32_e32 v177, v119
	v_exp_f32_e32 v179, v120
	v_exp_f32_e32 v254, v121
	v_add_f32_e32 v219, v0, v219
	v_add_f32_e32 v219, v177, v219
	v_cvt_pk_fp8_f32 v247, v0, v177
	v_add_f32_e32 v219, v179, v219
	v_add_f32_e32 v219, v254, v219
	v_cvt_pk_fp8_f32 v247, v179, v254 op_sel:[0,0,1]
	ds_read_b128 v[114:117], v213 offset:16384
	ds_read_b128 v[118:121], v214 offset:16384
	s_waitcnt lgkmcnt(2)
	v_mfma_scale_f32_32x32x64_f8f6f4 v[66:81], v[222:229], v[146:153], v[230:245], v194, v193 op_sel_hi:[0,0,0]
	ds_read_b128 v[222:225], v213 offset:20480
	ds_read_b128 v[226:229], v214 offset:20480
	v_exp_f32_e32 v0, v122
	v_exp_f32_e32 v177, v123
	v_exp_f32_e32 v179, v124
	v_exp_f32_e32 v254, v125
	v_add_f32_e32 v219, v0, v219
	v_add_f32_e32 v219, v177, v219
	v_cvt_pk_fp8_f32 v248, v0, v177
	v_add_f32_e32 v219, v179, v219
	v_add_f32_e32 v219, v254, v219
	v_cvt_pk_fp8_f32 v248, v179, v254 op_sel:[0,0,1]
	v_exp_f32_e32 v0, v126
	v_exp_f32_e32 v177, v127
	v_exp_f32_e32 v179, v128
	v_exp_f32_e32 v254, v129
	v_add_f32_e32 v219, v0, v219
	v_add_f32_e32 v219, v177, v219
	v_cvt_pk_fp8_f32 v249, v0, v177
	v_add_f32_e32 v219, v179, v219
	v_add_f32_e32 v219, v254, v219
	v_cvt_pk_fp8_f32 v249, v179, v254 op_sel:[0,0,1]
	ds_read_b128 v[122:125], v185 offset:32768
	ds_read_b128 v[126:129], v186 offset:32768
	s_waitcnt lgkmcnt(4)
	v_mfma_scale_f32_32x32x64_f8f6f4 v[82:97], v[114:121], v[138:145], v[82:97], v194, v193 op_sel_hi:[0,0,0]
	v_exp_f32_e32 v0, v98
	v_exp_f32_e32 v177, v99
	v_exp_f32_e32 v179, v100
	v_exp_f32_e32 v254, v101
	v_add_f32_e32 v219, v0, v219
	v_add_f32_e32 v219, v177, v219
	v_cvt_pk_fp8_f32 v250, v0, v177
	v_add_f32_e32 v219, v179, v219
	v_add_f32_e32 v219, v254, v219
	v_cvt_pk_fp8_f32 v250, v179, v254 op_sel:[0,0,1]
	s_waitcnt lgkmcnt(2)
	v_mfma_scale_f32_32x32x64_f8f6f4 v[66:81], v[222:229], v[138:145], v[66:81], v194, v193 op_sel_hi:[0,0,0]
	ds_read_b128 v[222:225], v185 offset:34816
	ds_read_b128 v[226:229], v186 offset:34816
	v_exp_f32_e32 v0, v102
	v_exp_f32_e32 v177, v103
	v_exp_f32_e32 v179, v104
	v_exp_f32_e32 v254, v105
	v_add_f32_e32 v219, v0, v219
	v_add_f32_e32 v219, v177, v219
	v_cvt_pk_fp8_f32 v251, v0, v177
	v_add_f32_e32 v219, v179, v219
	v_add_f32_e32 v219, v254, v219
	v_cvt_pk_fp8_f32 v251, v179, v254 op_sel:[0,0,1]
	v_exp_f32_e32 v0, v106
	v_exp_f32_e32 v177, v107
	v_exp_f32_e32 v179, v108
	v_exp_f32_e32 v254, v109
	v_add_f32_e32 v219, v0, v219
	v_add_f32_e32 v219, v177, v219
	v_cvt_pk_fp8_f32 v252, v0, v177
	v_add_f32_e32 v219, v179, v219
	v_add_f32_e32 v219, v254, v219
	v_cvt_pk_fp8_f32 v252, v179, v254 op_sel:[0,0,1]
	s_waitcnt lgkmcnt(2)
	v_mfma_scale_f32_32x32x64_f8f6f4 v[82:97], v[122:129], v[130:137], v[82:97], v194, v193 op_sel_hi:[0,0,0]
	v_exp_f32_e32 v0, v110
	v_exp_f32_e32 v177, v111
	v_exp_f32_e32 v179, v112
	v_exp_f32_e32 v254, v113
	v_add_f32_e32 v219, v0, v219
	v_add_f32_e32 v219, v177, v219
	v_cvt_pk_fp8_f32 v253, v0, v177
	v_add_f32_e32 v219, v179, v219
	v_add_f32_e32 v219, v254, v219
	v_cvt_pk_fp8_f32 v253, v179, v254 op_sel:[0,0,1]
	ds_read_b128 v[122:125], v185 offset:43008
	ds_read_b128 v[126:129], v186 offset:43008
	ds_read_b128 v[114:117], v185 offset:45056
	ds_read_b128 v[118:121], v186 offset:45056
	ds_read_b128 v[106:109], v185 offset:47104
	ds_read_b128 v[110:113], v186 offset:47104
	ds_read_b128 v[98:101], v185 offset:49152
	ds_read_b128 v[102:105], v186 offset:49152
	s_waitcnt lgkmcnt(8)
	v_mfma_scale_f32_32x32x64_f8f6f4 v[66:81], v[222:229], v[130:137], v[66:81], v194, v193 op_sel_hi:[0,0,0]
	v_mov_b32_e32 v0, v219
	s_nop 1
	v_permlane32_swap_b32_e32 v219, v0
	v_add_f32_e32 v219, v219, v0
	v_fma_f32 v209, v209, v221, v219
	v_add_u32_e32 v176, 0x2000, v176
	v_add_u32_e32 v178, 0x20000, v178
	s_mov_b64 s[20:21], 0x1000
	v_lshl_add_u64 v[180:181], v[180:181], 0, s[20:21]
	v_max_f32_e32 v177, v82, v83
	v_max3_f32 v177, v177, v84, v85
	v_max3_f32 v177, v177, v86, v87
	v_max3_f32 v177, v177, v88, v89
	v_max3_f32 v177, v177, v90, v91
	v_max3_f32 v177, v177, v92, v93
	v_max3_f32 v177, v177, v94, v95
	v_max3_f32 v177, v177, v96, v97
	s_waitcnt lgkmcnt(6)
	v_mfma_scale_f32_32x32x64_f8f6f4 v[50:65], v[246:253], v[122:129], v[50:65], v194, v194 op_sel_hi:[0,0,0]
	v_max_f32_e32 v0, v66, v67
	v_max3_f32 v0, v0, v68, v69
	v_max3_f32 v0, v0, v70, v71
	s_waitcnt lgkmcnt(4)
	v_mfma_scale_f32_32x32x64_f8f6f4 v[34:49], v[246:253], v[114:121], v[34:49], v194, v194 op_sel_hi:[0,0,0]
	v_max3_f32 v0, v0, v72, v73
	v_max3_f32 v0, v0, v74, v75
	v_max3_f32 v0, v0, v76, v77
	s_waitcnt lgkmcnt(2)
	v_mfma_scale_f32_32x32x64_f8f6f4 v[18:33], v[246:253], v[106:113], v[18:33], v194, v194 op_sel_hi:[0,0,0]
	v_max3_f32 v0, v0, v78, v79
	v_max3_f32 v0, v0, v80, v81
	v_max_f32_e32 v177, v177, v0
	v_mov_b32_e32 v0, v177
	v_mov_b32_e32 v218, 1.0
	s_waitcnt lgkmcnt(0)
	v_mfma_scale_f32_32x32x64_f8f6f4 v[2:17], v[246:253], v[98:105], v[2:17], v194, v194 op_sel_hi:[0,0,0]
	s_waitcnt vmcnt(0)
	s_waitcnt lgkmcnt(0)
	s_barrier
	v_permlane32_swap_b32_e32 v177, v0
	v_max_f32_e32 v177, v177, v0
	v_cmp_ge_f32_e32 vcc, s90, v177
	s_cmp_eq_u64 vcc, exec
	s_cbranch_scc0 .Lmla_h5_newmax
; __device__ __forceinline__ void finishSM9(f32x16& p0, f32x16& p1, float alpha, float& l_reg, v8i32& p8) {
; #pragma unroll
;   for (int r = 0; r < 16; ++r) { p0[r] = __builtin_amdgcn_exp2f(p0[r]); p1[r] = __builtin_amdgcn_exp2f(p1[r]); }
;   float ps = 0;
; #pragma unroll
;   for (int r = 0; r < 16; ++r) ps += p0[r];
; #pragma unroll
;   for (int r = 0; r < 16; ++r) ps += p1[r];
;   { auto rr = __builtin_amdgcn_permlane32_swap(__float_as_uint(ps), __float_as_uint(ps), false, false);
;     ps = __uint_as_float(rr[0]) + __uint_as_float(rr[1]); }
;   l_reg = l_reg * alpha + ps;
; #pragma unroll
;   for (int g = 0; g < 4; ++g) {
;     int w = __builtin_amdgcn_cvt_pk_fp8_f32(p0[4 * g], p0[4 * g + 1], 0, false); p8[g] = __builtin_amdgcn_cvt_pk_fp8_f32(p0[4 * g + 2], p0[4 * g + 3], w, true);
;     int u = __builtin_amdgcn_cvt_pk_fp8_f32(p1[4 * g], p1[4 * g + 1], 0, false); p8[4 + g] = __builtin_amdgcn_cvt_pk_fp8_f32(p1[4 * g + 2], p1[4 * g + 3], u, true); }
; }
; __device__ __forceinline__ void pv8(f32x16* o, const char* Vt, const v8i32 p8, int r32, int hi) {
;   const int sw = (r32 >> 2) & 3, a0 = r32 * 64 + (((hi * 2) ^ sw) << 4), a1 = r32 * 64 + (((hi * 2 + 1) ^ sw) << 4);
; #pragma unroll
;   for (int d0 = 0; d0 < 4; ++d0) {
;     const v8i32 vf = cat8(*reinterpret_cast<const v4i32*>(Vt + d0 * 2048 + a0), *reinterpret_cast<const v4i32*>(Vt + d0 * 2048 + a1));
;     o[d0] = __builtin_amdgcn_mfma_scale_f32_32x32x64_f8f6f4(p8, vf, o[d0], 0, 0, 0, 127, 0, 127); }
; }
; __device__ __forceinline__ void qkt9(f32x16& p0, f32x16& p1, const char* Kn, const char* Kr, const v8i32* qf, const float init, int r32, int hi) {
; #pragma unroll
;   for (int r = 0; r < 16; ++r) { p0[r] = init; p1[r] = init; }
; #pragma unroll
;   for (int s = 0; s < 2; ++s) { const int c0 = s * 4 + hi * 2;
;     const v8i32 a0 = cat8(*reinterpret_cast<const v4i32*>(Kn + KN8SW(r32, c0)), *reinterpret_cast<const v4i32*>(Kn + KN8SW(r32, c0 + 1)));
;     const v8i32 a1 = cat8(*reinterpret_cast<const v4i32*>(Kn + 4096 + KN8SW(r32, c0)), *reinterpret_cast<const v4i32*>(Kn + 4096 + KN8SW(r32, c0 + 1)));
;     p0 = __builtin_amdgcn_mfma_scale_f32_32x32x64_f8f6f4(a0, qf[s], p0, 0, 0, 0, 127, 0, 124);
;     p1 = __builtin_amdgcn_mfma_scale_f32_32x32x64_f8f6f4(a1, qf[s], p1, 0, 0, 0, 127, 0, 124); }
;   { const int c0 = hi * 2;
.Lmla_h5_cont:
	s_add_i32 s30, s30, 1
	s_cmpk_lt_u32 s30, 42
	s_cbranch_scc1 .LBB0_1321
	ds_read_b128 v[114:117], v215 offset:24576
	ds_read_b128 v[118:121], v216 offset:24576
	ds_read_b128 v[222:225], v215 offset:28672
	ds_read_b128 v[226:229], v216 offset:28672
	s_add_i32 m0, s98, 0xa800
	s_nop 0
	global_load_lds_dwordx4 v176, s[18:19]
	s_add_i32 m0, s98, 0xc800
	s_nop 0
	global_load_lds_dwordx4 v178, s[16:17]
	s_add_i32 m0, s98, 0xe800
	s_nop 0
	global_load_lds_dwordx4 v[180:181], off
	s_waitcnt lgkmcnt(2)
	v_mfma_scale_f32_32x32x64_f8f6f4 v[114:129], v[114:121], v[146:153], v[230:245], v194, v193 op_sel_hi:[0,0,0]
	v_exp_f32_e32 v0, v82
	v_exp_f32_e32 v177, v83
	v_exp_f32_e32 v179, v84
	v_exp_f32_e32 v254, v85
	v_add_f32_e32 v219, v0, v177
	v_cvt_pk_fp8_f32 v246, v0, v177
	v_add_f32_e32 v219, v179, v219
	v_add_f32_e32 v219, v254, v219
	v_cvt_pk_fp8_f32 v246, v179, v254 op_sel:[0,0,1]
	v_exp_f32_e32 v0, v86
	v_exp_f32_e32 v177, v87
	v_exp_f32_e32 v179, v88
	v_exp_f32_e32 v254, v89
	v_add_f32_e32 v219, v0, v219
	v_add_f32_e32 v219, v177, v219
	v_cvt_pk_fp8_f32 v247, v0, v177
	v_add_f32_e32 v219, v179, v219
	v_add_f32_e32 v219, v254, v219
	v_cvt_pk_fp8_f32 v247, v179, v254 op_sel:[0,0,1]
	ds_read_b128 v[82:85], v213 offset:24576
	ds_read_b128 v[86:89], v214 offset:24576
	s_waitcnt lgkmcnt(2)
	v_mfma_scale_f32_32x32x64_f8f6f4 v[98:113], v[222:229], v[146:153], v[230:245], v194, v193 op_sel_hi:[0,0,0]
	ds_read_b128 v[222:225], v213 offset:28672
	ds_read_b128 v[226:229], v214 offset:28672
	v_exp_f32_e32 v0, v90
	v_exp_f32_e32 v177, v91
	v_exp_f32_e32 v179, v92
	v_exp_f32_e32 v254, v93
	v_add_f32_e32 v219, v0, v219
	v_add_f32_e32 v219, v177, v219
	v_cvt_pk_fp8_f32 v248, v0, v177
	v_add_f32_e32 v219, v179, v219
	v_add_f32_e32 v219, v254, v219
	v_cvt_pk_fp8_f32 v248, v179, v254 op_sel:[0,0,1]
	v_exp_f32_e32 v0, v94
	v_exp_f32_e32 v177, v95
	v_exp_f32_e32 v179, v96
	v_exp_f32_e32 v254, v97
	v_add_f32_e32 v219, v0, v219
	v_add_f32_e32 v219, v177, v219
	v_cvt_pk_fp8_f32 v249, v0, v177
	v_add_f32_e32 v219, v179, v219
	v_add_f32_e32 v219, v254, v219
	v_cvt_pk_fp8_f32 v249, v179, v254 op_sel:[0,0,1]
	ds_read_b128 v[90:93], v185 offset:36864
	ds_read_b128 v[94:97], v186 offset:36864
	s_waitcnt lgkmcnt(4)
	v_mfma_scale_f32_32x32x64_f8f6f4 v[114:129], v[82:89], v[138:145], v[114:129], v194, v193 op_sel_hi:[0,0,0]
	v_exp_f32_e32 v0, v66
	v_exp_f32_e32 v177, v67
	v_exp_f32_e32 v179, v68
	v_exp_f32_e32 v254, v69
	v_add_f32_e32 v219, v0, v219
	v_add_f32_e32 v219, v177, v219
	v_cvt_pk_fp8_f32 v250, v0, v177
	v_add_f32_e32 v219, v179, v219
	v_add_f32_e32 v219, v254, v219
	v_cvt_pk_fp8_f32 v250, v179, v254 op_sel:[0,0,1]
	s_waitcnt lgkmcnt(2)
	v_mfma_scale_f32_32x32x64_f8f6f4 v[98:113], v[222:229], v[138:145], v[98:113], v194, v193 op_sel_hi:[0,0,0]
	ds_read_b128 v[222:225], v185 offset:38912
	ds_read_b128 v[226:229], v186 offset:38912
	v_exp_f32_e32 v0, v70
	v_exp_f32_e32 v177, v71
	v_exp_f32_e32 v179, v72
	v_exp_f32_e32 v254, v73
	v_add_f32_e32 v219, v0, v219
	v_add_f32_e32 v219, v177, v219
	v_cvt_pk_fp8_f32 v251, v0, v177
	v_add_f32_e32 v219, v179, v219
	v_add_f32_e32 v219, v254, v219
	v_cvt_pk_fp8_f32 v251, v179, v254 op_sel:[0,0,1]
	v_exp_f32_e32 v0, v74
	v_exp_f32_e32 v177, v75
	v_exp_f32_e32 v179, v76
	v_exp_f32_e32 v254, v77
	v_add_f32_e32 v219, v0, v219
	v_add_f32_e32 v219, v177, v219
	v_cvt_pk_fp8_f32 v252, v0, v177
	v_add_f32_e32 v219, v179, v219
	v_add_f32_e32 v219, v254, v219
	v_cvt_pk_fp8_f32 v252, v179, v254 op_sel:[0,0,1]
	s_waitcnt lgkmcnt(2)
	v_mfma_scale_f32_32x32x64_f8f6f4 v[114:129], v[90:97], v[130:137], v[114:129], v194, v193 op_sel_hi:[0,0,0]
	v_exp_f32_e32 v0, v78
	v_exp_f32_e32 v177, v79
	v_exp_f32_e32 v179, v80
	v_exp_f32_e32 v254, v81
	v_add_f32_e32 v219, v0, v219
	v_add_f32_e32 v219, v177, v219
	v_cvt_pk_fp8_f32 v253, v0, v177
	v_add_f32_e32 v219, v179, v219
	v_add_f32_e32 v219, v254, v219
	v_cvt_pk_fp8_f32 v253, v179, v254 op_sel:[0,0,1]
	ds_read_b128 v[90:93], v185 offset:0
	ds_read_b128 v[94:97], v186 offset:0
	ds_read_b128 v[82:85], v185 offset:2048
	ds_read_b128 v[86:89], v186 offset:2048
	ds_read_b128 v[74:77], v185 offset:4096
	ds_read_b128 v[78:81], v186 offset:4096
	ds_read_b128 v[66:69], v185 offset:6144
	ds_read_b128 v[70:73], v186 offset:6144
	s_waitcnt lgkmcnt(8)
	v_mfma_scale_f32_32x32x64_f8f6f4 v[98:113], v[222:229], v[130:137], v[98:113], v194, v193 op_sel_hi:[0,0,0]
	v_mov_b32_e32 v0, v219
	s_nop 1
	v_permlane32_swap_b32_e32 v219, v0
	v_add_f32_e32 v219, v219, v0
	v_fma_f32 v209, v209, v218, v219
	v_add_u32_e32 v176, 0x2000, v176
	v_add_u32_e32 v178, 0x20000, v178
	s_mov_b64 s[20:21], 0x1000
	v_lshl_add_u64 v[180:181], v[180:181], 0, s[20:21]
	v_max_f32_e32 v177, v114, v115
	v_max3_f32 v177, v177, v116, v117
	v_max3_f32 v177, v177, v118, v119
	v_max3_f32 v177, v177, v120, v121
	v_max3_f32 v177, v177, v122, v123
	v_max3_f32 v177, v177, v124, v125
	v_max3_f32 v177, v177, v126, v127
	v_max3_f32 v177, v177, v128, v129
	s_waitcnt lgkmcnt(6)
	v_mfma_scale_f32_32x32x64_f8f6f4 v[50:65], v[246:253], v[90:97], v[50:65], v194, v194 op_sel_hi:[0,0,0]
	v_max_f32_e32 v0, v98, v99
	v_max3_f32 v0, v0, v100, v101
	v_max3_f32 v0, v0, v102, v103
	s_waitcnt lgkmcnt(4)
	v_mfma_scale_f32_32x32x64_f8f6f4 v[34:49], v[246:253], v[82:89], v[34:49], v194, v194 op_sel_hi:[0,0,0]
	v_max3_f32 v0, v0, v104, v105
	v_max3_f32 v0, v0, v106, v107
	v_max3_f32 v0, v0, v108, v109
	s_waitcnt lgkmcnt(2)
	v_mfma_scale_f32_32x32x64_f8f6f4 v[18:33], v[246:253], v[74:81], v[18:33], v194, v194 op_sel_hi:[0,0,0]
	v_max3_f32 v0, v0, v110, v111
	v_max3_f32 v0, v0, v112, v113
	v_max_f32_e32 v177, v177, v0
	v_mov_b32_e32 v0, v177
	v_mov_b32_e32 v221, 1.0
	s_waitcnt lgkmcnt(0)
	v_mfma_scale_f32_32x32x64_f8f6f4 v[2:17], v[246:253], v[66:73], v[2:17], v194, v194 op_sel_hi:[0,0,0]
	s_waitcnt vmcnt(0)
	s_waitcnt lgkmcnt(0)
	s_barrier
	v_permlane32_swap_b32_e32 v177, v0
	v_max_f32_e32 v177, v177, v0
	v_cmp_ge_f32_e32 vcc, s90, v177
	s_cmp_eq_u64 vcc, exec
	s_cbranch_scc0 .Lmla_p0_newmax

; __device__ __forceinline__ void finishSM9(f32x16& p0, f32x16& p1, float alpha, float& l_reg, v8i32& p8) {
; #pragma unroll
;   for (int r = 0; r < 16; ++r) { p0[r] = __builtin_amdgcn_exp2f(p0[r]); p1[r] = __builtin_amdgcn_exp2f(p1[r]); }
;   float ps = 0;
; #pragma unroll
;   for (int r = 0; r < 16; ++r) ps += p0[r];
; #pragma unroll
;   for (int r = 0; r < 16; ++r) ps += p1[r];
;   { auto rr = __builtin_amdgcn_permlane32_swap(__float_as_uint(ps), __float_as_uint(ps), false, false);
;     ps = __uint_as_float(rr[0]) + __uint_as_float(rr[1]); }
;   l_reg = l_reg * alpha + ps;
; #pragma unroll
;   for (int g = 0; g < 4; ++g) {
;     int w = __builtin_amdgcn_cvt_pk_fp8_f32(p0[4 * g], p0[4 * g + 1], 0, false); p8[g] = __builtin_amdgcn_cvt_pk_fp8_f32(p0[4 * g + 2], p0[4 * g + 3], w, true);
;     int u = __builtin_amdgcn_cvt_pk_fp8_f32(p1[4 * g], p1[4 * g + 1], 0, false); p8[4 + g] = __builtin_amdgcn_cvt_pk_fp8_f32(p1[4 * g + 2], p1[4 * g + 3], u, true); }
; }
; __device__ __forceinline__ void pv8(f32x16* o, const char* Vt, const v8i32 p8, int r32, int hi) {
;   const int sw = (r32 >> 2) & 3, a0 = r32 * 64 + (((hi * 2) ^ sw) << 4), a1 = r32 * 64 + (((hi * 2 + 1) ^ sw) << 4);
; #pragma unroll
;   for (int d0 = 0; d0 < 4; ++d0) {
;     const v8i32 vf = cat8(*reinterpret_cast<const v4i32*>(Vt + d0 * 2048 + a0), *reinterpret_cast<const v4i32*>(Vt + d0 * 2048 + a1));
;     o[d0] = __builtin_amdgcn_mfma_scale_f32_32x32x64_f8f6f4(p8, vf, o[d0], 0, 0, 0, 127, 0, 127); }
; }
; __device__ __forceinline__ void qkt9(f32x16& p0, f32x16& p1, const char* Kn, const char* Kr, const v8i32* qf, const float init, int r32, int hi) {
; #pragma unroll
;   for (int r = 0; r < 16; ++r) { p0[r] = init; p1[r] = init; }
; #pragma unroll
;   for (int s = 0; s < 2; ++s) { const int c0 = s * 4 + hi * 2;
;     const v8i32 a0 = cat8(*reinterpret_cast<const v4i32*>(Kn + KN8SW(r32, c0)), *reinterpret_cast<const v4i32*>(Kn + KN8SW(r32, c0 + 1)));
;     const v8i32 a1 = cat8(*reinterpret_cast<const v4i32*>(Kn + 4096 + KN8SW(r32, c0)), *reinterpret_cast<const v4i32*>(Kn + 4096 + KN8SW(r32, c0 + 1)));
;     p0 = __builtin_amdgcn_mfma_scale_f32_32x32x64_f8f6f4(a0, qf[s], p0, 0, 0, 0, 127, 0, 124);
;     p1 = __builtin_amdgcn_mfma_scale_f32_32x32x64_f8f6f4(a1, qf[s], p1, 0, 0, 0, 127, 0, 124); }
;   { const int c0 = hi * 2;
.Lmla_stag_loop:
	ds_read_b128 v[114:117], v215 offset:24576
	ds_read_b128 v[118:121], v216 offset:24576
	ds_read_b128 v[222:225], v215 offset:28672
	ds_read_b128 v[226:229], v216 offset:28672
	s_waitcnt lgkmcnt(2)
	v_mfma_scale_f32_32x32x64_f8f6f4 v[114:129], v[114:121], v[146:153], v[230:245], v194, v193 op_sel_hi:[0,0,0]
	v_exp_f32_e32 v0, v82
	v_exp_f32_e32 v177, v83
	v_exp_f32_e32 v179, v84
	v_exp_f32_e32 v254, v85
	v_add_f32_e32 v219, v0, v177
	v_cvt_pk_fp8_f32 v246, v0, v177
	v_add_f32_e32 v219, v179, v219
	v_add_f32_e32 v219, v254, v219
	v_cvt_pk_fp8_f32 v246, v179, v254 op_sel:[0,0,1]
	v_exp_f32_e32 v0, v86
	v_exp_f32_e32 v177, v87
	v_exp_f32_e32 v179, v88
	v_exp_f32_e32 v254, v89
	v_add_f32_e32 v219, v0, v219
	v_add_f32_e32 v219, v177, v219
	v_cvt_pk_fp8_f32 v247, v0, v177
	v_add_f32_e32 v219, v179, v219
	v_add_f32_e32 v219, v254, v219
	v_cvt_pk_fp8_f32 v247, v179, v254 op_sel:[0,0,1]
	ds_read_b128 v[82:85], v213 offset:24576
	ds_read_b128 v[86:89], v214 offset:24576
	s_waitcnt lgkmcnt(2)
	v_mfma_scale_f32_32x32x64_f8f6f4 v[98:113], v[222:229], v[146:153], v[230:245], v194, v193 op_sel_hi:[0,0,0]
	ds_read_b128 v[222:225], v213 offset:28672
	ds_read_b128 v[226:229], v214 offset:28672
	v_exp_f32_e32 v0, v90
	v_exp_f32_e32 v177, v91
	v_exp_f32_e32 v179, v92
	v_exp_f32_e32 v254, v93
	v_add_f32_e32 v219, v0, v219
	v_add_f32_e32 v219, v177, v219
	v_cvt_pk_fp8_f32 v248, v0, v177
	v_add_f32_e32 v219, v179, v219
	v_add_f32_e32 v219, v254, v219
	v_cvt_pk_fp8_f32 v248, v179, v254 op_sel:[0,0,1]
	v_exp_f32_e32 v0, v94
	v_exp_f32_e32 v177, v95
	v_exp_f32_e32 v179, v96
	v_exp_f32_e32 v254, v97
	v_add_f32_e32 v219, v0, v219
	v_add_f32_e32 v219, v177, v219
	v_cvt_pk_fp8_f32 v249, v0, v177
	v_add_f32_e32 v219, v179, v219
	v_add_f32_e32 v219, v254, v219
	v_cvt_pk_fp8_f32 v249, v179, v254 op_sel:[0,0,1]
	ds_read_b128 v[90:93], v185 offset:36864
	ds_read_b128 v[94:97], v186 offset:36864
	s_waitcnt lgkmcnt(4)
	v_mfma_scale_f32_32x32x64_f8f6f4 v[114:129], v[82:89], v[138:145], v[114:129], v194, v193 op_sel_hi:[0,0,0]
	v_exp_f32_e32 v0, v66
	v_exp_f32_e32 v177, v67
	v_exp_f32_e32 v179, v68
	v_exp_f32_e32 v254, v69
	v_add_f32_e32 v219, v0, v219
	v_add_f32_e32 v219, v177, v219
	v_cvt_pk_fp8_f32 v250, v0, v177
	v_add_f32_e32 v219, v179, v219
	v_add_f32_e32 v219, v254, v219
	v_cvt_pk_fp8_f32 v250, v179, v254 op_sel:[0,0,1]
	s_waitcnt lgkmcnt(2)
	v_mfma_scale_f32_32x32x64_f8f6f4 v[98:113], v[222:229], v[138:145], v[98:113], v194, v193 op_sel_hi:[0,0,0]
	ds_read_b128 v[222:225], v185 offset:38912
	ds_read_b128 v[226:229], v186 offset:38912
	v_exp_f32_e32 v0, v70
	v_exp_f32_e32 v177, v71
	v_exp_f32_e32 v179, v72
	v_exp_f32_e32 v254, v73
	v_add_f32_e32 v219, v0, v219
	v_add_f32_e32 v219, v177, v219
	v_cvt_pk_fp8_f32 v251, v0, v177
	v_add_f32_e32 v219, v179, v219
	v_add_f32_e32 v219, v254, v219
	v_cvt_pk_fp8_f32 v251, v179, v254 op_sel:[0,0,1]
	v_exp_f32_e32 v0, v74
	v_exp_f32_e32 v177, v75
	v_exp_f32_e32 v179, v76
	v_exp_f32_e32 v254, v77
	v_add_f32_e32 v219, v0, v219
	v_add_f32_e32 v219, v177, v219
	v_cvt_pk_fp8_f32 v252, v0, v177
	v_add_f32_e32 v219, v179, v219
	v_add_f32_e32 v219, v254, v219
	v_cvt_pk_fp8_f32 v252, v179, v254 op_sel:[0,0,1]
	s_waitcnt lgkmcnt(2)
	v_mfma_scale_f32_32x32x64_f8f6f4 v[114:129], v[90:97], v[130:137], v[114:129], v194, v193 op_sel_hi:[0,0,0]
	v_exp_f32_e32 v0, v78
	v_exp_f32_e32 v177, v79
	v_exp_f32_e32 v179, v80
	v_exp_f32_e32 v254, v81
	v_add_f32_e32 v219, v0, v219
	v_add_f32_e32 v219, v177, v219
	v_cvt_pk_fp8_f32 v253, v0, v177
	v_add_f32_e32 v219, v179, v219
	v_add_f32_e32 v219, v254, v219
	v_cvt_pk_fp8_f32 v253, v179, v254 op_sel:[0,0,1]
	ds_read_b128 v[90:93], v185 offset:0
	ds_read_b128 v[94:97], v186 offset:0
	ds_read_b128 v[82:85], v185 offset:2048
	ds_read_b128 v[86:89], v186 offset:2048
	ds_read_b128 v[74:77], v185 offset:4096
	ds_read_b128 v[78:81], v186 offset:4096
	ds_read_b128 v[66:69], v185 offset:6144
	ds_read_b128 v[70:73], v186 offset:6144
	s_waitcnt lgkmcnt(8)
	v_mfma_scale_f32_32x32x64_f8f6f4 v[98:113], v[222:229], v[130:137], v[98:113], v194, v193 op_sel_hi:[0,0,0]
	v_mov_b32_e32 v0, v219
	s_nop 1
	v_permlane32_swap_b32_e32 v219, v0
	v_add_f32_e32 v219, v219, v0
	v_fma_f32 v209, v209, v218, v219
	v_max_f32_e32 v177, v114, v115
	v_max3_f32 v177, v177, v116, v117
	v_max3_f32 v177, v177, v118, v119
	v_max3_f32 v177, v177, v120, v121
	v_max3_f32 v177, v177, v122, v123
	v_max3_f32 v177, v177, v124, v125
	v_max3_f32 v177, v177, v126, v127
	v_max3_f32 v177, v177, v128, v129
	s_waitcnt lgkmcnt(6)
	v_mfma_scale_f32_32x32x64_f8f6f4 v[50:65], v[246:253], v[90:97], v[50:65], v194, v194 op_sel_hi:[0,0,0]
	s_waitcnt lgkmcnt(4)
	v_mfma_scale_f32_32x32x64_f8f6f4 v[34:49], v[246:253], v[82:89], v[34:49], v194, v194 op_sel_hi:[0,0,0]
	s_waitcnt vmcnt(0)
	s_waitcnt lgkmcnt(0)
	s_barrier
	v_max_f32_e32 v0, v98, v99
	v_max3_f32 v0, v0, v100, v101
	v_max3_f32 v0, v0, v102, v103
	v_max3_f32 v0, v0, v104, v105
	s_waitcnt lgkmcnt(2)
	v_mfma_scale_f32_32x32x64_f8f6f4 v[18:33], v[246:253], v[74:81], v[18:33], v194, v194 op_sel_hi:[0,0,0]
	s_add_i32 m0, s98, 0x0
	s_nop 0
	global_load_lds_dwordx4 v176, s[18:19]
	s_add_i32 m0, s98, 0x4000
	s_nop 0
	global_load_lds_dwordx4 v178, s[16:17]
	v_add_u32_e32 v176, 0x2000, v176
	v_add_u32_e32 v178, 0x20000, v178
	v_max3_f32 v0, v0, v106, v107
	v_max3_f32 v0, v0, v108, v109
	v_max3_f32 v0, v0, v110, v111
	v_max3_f32 v0, v0, v112, v113
	s_waitcnt lgkmcnt(0)
	v_mfma_scale_f32_32x32x64_f8f6f4 v[2:17], v[246:253], v[66:73], v[2:17], v194, v194 op_sel_hi:[0,0,0]
	v_max_f32_e32 v177, v177, v0
	v_mov_b32_e32 v0, v177
	v_mov_b32_e32 v221, 1.0
	s_nop 0
	v_permlane32_swap_b32_e32 v177, v0
	v_max_f32_e32 v177, v177, v0
	v_cmp_ge_f32_e32 vcc, s90, v177
	s_cmp_eq_u64 vcc, exec
	s_cbranch_scc0 .Lmla_s0_newmax
; __device__ __forceinline__ void finishSM9(f32x16& p0, f32x16& p1, float alpha, float& l_reg, v8i32& p8) {
; #pragma unroll
;   for (int r = 0; r < 16; ++r) { p0[r] = __builtin_amdgcn_exp2f(p0[r]); p1[r] = __builtin_amdgcn_exp2f(p1[r]); }
;   float ps = 0;
; #pragma unroll
;   for (int r = 0; r < 16; ++r) ps += p0[r];
; #pragma unroll
;   for (int r = 0; r < 16; ++r) ps += p1[r];
;   { auto rr = __builtin_amdgcn_permlane32_swap(__float_as_uint(ps), __float_as_uint(ps), false, false);
;     ps = __uint_as_float(rr[0]) + __uint_as_float(rr[1]); }
;   l_reg = l_reg * alpha + ps;
; #pragma unroll
;   for (int g = 0; g < 4; ++g) {
;     int w = __builtin_amdgcn_cvt_pk_fp8_f32(p0[4 * g], p0[4 * g + 1], 0, false); p8[g] = __builtin_amdgcn_cvt_pk_fp8_f32(p0[4 * g + 2], p0[4 * g + 3], w, true);
;     int u = __builtin_amdgcn_cvt_pk_fp8_f32(p1[4 * g], p1[4 * g + 1], 0, false); p8[4 + g] = __builtin_amdgcn_cvt_pk_fp8_f32(p1[4 * g + 2], p1[4 * g + 3], u, true); }
; }
; __device__ __forceinline__ void pv8(f32x16* o, const char* Vt, const v8i32 p8, int r32, int hi) {
;   const int sw = (r32 >> 2) & 3, a0 = r32 * 64 + (((hi * 2) ^ sw) << 4), a1 = r32 * 64 + (((hi * 2 + 1) ^ sw) << 4);
; #pragma unroll
;   for (int d0 = 0; d0 < 4; ++d0) {
;     const v8i32 vf = cat8(*reinterpret_cast<const v4i32*>(Vt + d0 * 2048 + a0), *reinterpret_cast<const v4i32*>(Vt + d0 * 2048 + a1));
;     o[d0] = __builtin_amdgcn_mfma_scale_f32_32x32x64_f8f6f4(p8, vf, o[d0], 0, 0, 0, 127, 0, 127); }
; }
; __device__ __forceinline__ void qkt9(f32x16& p0, f32x16& p1, const char* Kn, const char* Kr, const v8i32* qf, const float init, int r32, int hi) {
; #pragma unroll
;   for (int r = 0; r < 16; ++r) { p0[r] = init; p1[r] = init; }
; #pragma unroll
;   for (int s = 0; s < 2; ++s) { const int c0 = s * 4 + hi * 2;
;     const v8i32 a0 = cat8(*reinterpret_cast<const v4i32*>(Kn + KN8SW(r32, c0)), *reinterpret_cast<const v4i32*>(Kn + KN8SW(r32, c0 + 1)));
;     const v8i32 a1 = cat8(*reinterpret_cast<const v4i32*>(Kn + 4096 + KN8SW(r32, c0)), *reinterpret_cast<const v4i32*>(Kn + 4096 + KN8SW(r32, c0 + 1)));
;     p0 = __builtin_amdgcn_mfma_scale_f32_32x32x64_f8f6f4(a0, qf[s], p0, 0, 0, 0, 127, 0, 124);
;     p1 = __builtin_amdgcn_mfma_scale_f32_32x32x64_f8f6f4(a1, qf[s], p1, 0, 0, 0, 127, 0, 124); }
;   { const int c0 = hi * 2;
.Lmla_s0_cont:
	ds_read_b128 v[82:85], v215 offset:51200
	ds_read_b128 v[86:89], v216 offset:51200
	ds_read_b128 v[222:225], v215 offset:55296
	ds_read_b128 v[226:229], v216 offset:55296
	s_waitcnt lgkmcnt(2)
	v_mfma_scale_f32_32x32x64_f8f6f4 v[82:97], v[82:89], v[146:153], v[230:245], v194, v193 op_sel_hi:[0,0,0]
	v_exp_f32_e32 v0, v114
	v_exp_f32_e32 v177, v115
	v_exp_f32_e32 v179, v116
	v_exp_f32_e32 v254, v117
	v_add_f32_e32 v219, v0, v177
	v_cvt_pk_fp8_f32 v246, v0, v177
	v_add_f32_e32 v219, v179, v219
	v_add_f32_e32 v219, v254, v219
	v_cvt_pk_fp8_f32 v246, v179, v254 op_sel:[0,0,1]
	v_exp_f32_e32 v0, v118
	v_exp_f32_e32 v177, v119
	v_exp_f32_e32 v179, v120
	v_exp_f32_e32 v254, v121
	v_add_f32_e32 v219, v0, v219
	v_add_f32_e32 v219, v177, v219
	v_cvt_pk_fp8_f32 v247, v0, v177
	v_add_f32_e32 v219, v179, v219
	v_add_f32_e32 v219, v254, v219
	v_cvt_pk_fp8_f32 v247, v179, v254 op_sel:[0,0,1]
	ds_read_b128 v[114:117], v213 offset:51200
	ds_read_b128 v[118:121], v214 offset:51200
	s_waitcnt lgkmcnt(2)
	v_mfma_scale_f32_32x32x64_f8f6f4 v[66:81], v[222:229], v[146:153], v[230:245], v194, v193 op_sel_hi:[0,0,0]
	ds_read_b128 v[222:225], v213 offset:55296
	ds_read_b128 v[226:229], v214 offset:55296
	v_exp_f32_e32 v0, v122
	v_exp_f32_e32 v177, v123
	v_exp_f32_e32 v179, v124
	v_exp_f32_e32 v254, v125
	v_add_f32_e32 v219, v0, v219
	v_add_f32_e32 v219, v177, v219
	v_cvt_pk_fp8_f32 v248, v0, v177
	v_add_f32_e32 v219, v179, v219
	v_add_f32_e32 v219, v254, v219
	v_cvt_pk_fp8_f32 v248, v179, v254 op_sel:[0,0,1]
	v_exp_f32_e32 v0, v126
	v_exp_f32_e32 v177, v127
	v_exp_f32_e32 v179, v128
	v_exp_f32_e32 v254, v129
	v_add_f32_e32 v219, v0, v219
	v_add_f32_e32 v219, v177, v219
	v_cvt_pk_fp8_f32 v249, v0, v177
	v_add_f32_e32 v219, v179, v219
	v_add_f32_e32 v219, v254, v219
	v_cvt_pk_fp8_f32 v249, v179, v254 op_sel:[0,0,1]
	ds_read_b128 v[122:125], v185 offset:59392
	ds_read_b128 v[126:129], v186 offset:59392
	s_waitcnt lgkmcnt(4)
	v_mfma_scale_f32_32x32x64_f8f6f4 v[82:97], v[114:121], v[138:145], v[82:97], v194, v193 op_sel_hi:[0,0,0]
	v_exp_f32_e32 v0, v98
	v_exp_f32_e32 v177, v99
	v_exp_f32_e32 v179, v100
	v_exp_f32_e32 v254, v101
	v_add_f32_e32 v219, v0, v219
	v_add_f32_e32 v219, v177, v219
	v_cvt_pk_fp8_f32 v250, v0, v177
	v_add_f32_e32 v219, v179, v219
	v_add_f32_e32 v219, v254, v219
	v_cvt_pk_fp8_f32 v250, v179, v254 op_sel:[0,0,1]
	s_waitcnt lgkmcnt(2)
	v_mfma_scale_f32_32x32x64_f8f6f4 v[66:81], v[222:229], v[138:145], v[66:81], v194, v193 op_sel_hi:[0,0,0]
	ds_read_b128 v[222:225], v185 offset:61440
	ds_read_b128 v[226:229], v186 offset:61440
	v_exp_f32_e32 v0, v102
	v_exp_f32_e32 v177, v103
	v_exp_f32_e32 v179, v104
	v_exp_f32_e32 v254, v105
	v_add_f32_e32 v219, v0, v219
	v_add_f32_e32 v219, v177, v219
	v_cvt_pk_fp8_f32 v251, v0, v177
	v_add_f32_e32 v219, v179, v219
	v_add_f32_e32 v219, v254, v219
	v_cvt_pk_fp8_f32 v251, v179, v254 op_sel:[0,0,1]
	v_exp_f32_e32 v0, v106
	v_exp_f32_e32 v177, v107
	v_exp_f32_e32 v179, v108
	v_exp_f32_e32 v254, v109
	v_add_f32_e32 v219, v0, v219
	v_add_f32_e32 v219, v177, v219
	v_cvt_pk_fp8_f32 v252, v0, v177
	v_add_f32_e32 v219, v179, v219
	v_add_f32_e32 v219, v254, v219
	v_cvt_pk_fp8_f32 v252, v179, v254 op_sel:[0,0,1]
	s_waitcnt lgkmcnt(2)
	v_mfma_scale_f32_32x32x64_f8f6f4 v[82:97], v[122:129], v[130:137], v[82:97], v194, v193 op_sel_hi:[0,0,0]
	v_exp_f32_e32 v0, v110
	v_exp_f32_e32 v177, v111
	v_exp_f32_e32 v179, v112
	v_exp_f32_e32 v254, v113
	v_add_f32_e32 v219, v0, v219
	v_add_f32_e32 v219, v177, v219
	v_cvt_pk_fp8_f32 v253, v0, v177
	v_add_f32_e32 v219, v179, v219
	v_add_f32_e32 v219, v254, v219
	v_cvt_pk_fp8_f32 v253, v179, v254 op_sel:[0,0,1]
	ds_read_b128 v[122:125], v185 offset:8192
	ds_read_b128 v[126:129], v186 offset:8192
	ds_read_b128 v[114:117], v185 offset:10240
	ds_read_b128 v[118:121], v186 offset:10240
	ds_read_b128 v[106:109], v185 offset:12288
	ds_read_b128 v[110:113], v186 offset:12288
	ds_read_b128 v[98:101], v185 offset:14336
	ds_read_b128 v[102:105], v186 offset:14336
	s_waitcnt lgkmcnt(8)
	v_mfma_scale_f32_32x32x64_f8f6f4 v[66:81], v[222:229], v[130:137], v[66:81], v194, v193 op_sel_hi:[0,0,0]
	v_mov_b32_e32 v0, v219
	s_nop 1
	v_permlane32_swap_b32_e32 v219, v0
	v_add_f32_e32 v219, v219, v0
	v_fma_f32 v209, v209, v221, v219
	v_max_f32_e32 v177, v82, v83
	v_max3_f32 v177, v177, v84, v85
	v_max3_f32 v177, v177, v86, v87
	v_max3_f32 v177, v177, v88, v89
	v_max3_f32 v177, v177, v90, v91
	v_max3_f32 v177, v177, v92, v93
	v_max3_f32 v177, v177, v94, v95
	v_max3_f32 v177, v177, v96, v97
	s_waitcnt lgkmcnt(6)
	v_mfma_scale_f32_32x32x64_f8f6f4 v[50:65], v[246:253], v[122:129], v[50:65], v194, v194 op_sel_hi:[0,0,0]
	s_waitcnt lgkmcnt(4)
	v_mfma_scale_f32_32x32x64_f8f6f4 v[34:49], v[246:253], v[114:121], v[34:49], v194, v194 op_sel_hi:[0,0,0]
	s_waitcnt vmcnt(0)
	s_waitcnt lgkmcnt(0)
	s_barrier
	v_max_f32_e32 v0, v66, v67
	v_max3_f32 v0, v0, v68, v69
	v_max3_f32 v0, v0, v70, v71
	v_max3_f32 v0, v0, v72, v73
	s_waitcnt lgkmcnt(2)
	v_mfma_scale_f32_32x32x64_f8f6f4 v[18:33], v[246:253], v[106:113], v[18:33], v194, v194 op_sel_hi:[0,0,0]
	s_add_i32 m0, s98, 0x2000
	s_nop 0
	global_load_lds_dwordx4 v176, s[18:19]
	s_add_i32 m0, s98, 0x6000
	s_nop 0
	global_load_lds_dwordx4 v178, s[16:17]
	v_add_u32_e32 v176, 0x2000, v176
	v_add_u32_e32 v178, 0x20000, v178
	v_max3_f32 v0, v0, v74, v75
	v_max3_f32 v0, v0, v76, v77
	v_max3_f32 v0, v0, v78, v79
	v_max3_f32 v0, v0, v80, v81
	s_waitcnt lgkmcnt(0)
	v_mfma_scale_f32_32x32x64_f8f6f4 v[2:17], v[246:253], v[98:105], v[2:17], v194, v194 op_sel_hi:[0,0,0]
	v_max_f32_e32 v177, v177, v0
	v_mov_b32_e32 v0, v177
	v_mov_b32_e32 v218, 1.0
	s_nop 0
	v_permlane32_swap_b32_e32 v177, v0
	v_max_f32_e32 v177, v177, v0
	v_cmp_ge_f32_e32 vcc, s90, v177
	s_cmp_eq_u64 vcc, exec
	s_cbranch_scc0 .Lmla_s1_newmax
; __device__ __forceinline__ void finishSM9(f32x16& p0, f32x16& p1, float alpha, float& l_reg, v8i32& p8) {
; #pragma unroll
;   for (int r = 0; r < 16; ++r) { p0[r] = __builtin_amdgcn_exp2f(p0[r]); p1[r] = __builtin_amdgcn_exp2f(p1[r]); }
;   float ps = 0;
; #pragma unroll
;   for (int r = 0; r < 16; ++r) ps += p0[r];
; #pragma unroll
;   for (int r = 0; r < 16; ++r) ps += p1[r];
;   { auto rr = __builtin_amdgcn_permlane32_swap(__float_as_uint(ps), __float_as_uint(ps), false, false);
;     ps = __uint_as_float(rr[0]) + __uint_as_float(rr[1]); }
;   l_reg = l_reg * alpha + ps;
; #pragma unroll
;   for (int g = 0; g < 4; ++g) {
;     int w = __builtin_amdgcn_cvt_pk_fp8_f32(p0[4 * g], p0[4 * g + 1], 0, false); p8[g] = __builtin_amdgcn_cvt_pk_fp8_f32(p0[4 * g + 2], p0[4 * g + 3], w, true);
;     int u = __builtin_amdgcn_cvt_pk_fp8_f32(p1[4 * g], p1[4 * g + 1], 0, false); p8[4 + g] = __builtin_amdgcn_cvt_pk_fp8_f32(p1[4 * g + 2], p1[4 * g + 3], u, true); }
; }
; __device__ __forceinline__ void pv8(f32x16* o, const char* Vt, const v8i32 p8, int r32, int hi) {
;   const int sw = (r32 >> 2) & 3, a0 = r32 * 64 + (((hi * 2) ^ sw) << 4), a1 = r32 * 64 + (((hi * 2 + 1) ^ sw) << 4);
; #pragma unroll
;   for (int d0 = 0; d0 < 4; ++d0) {
;     const v8i32 vf = cat8(*reinterpret_cast<const v4i32*>(Vt + d0 * 2048 + a0), *reinterpret_cast<const v4i32*>(Vt + d0 * 2048 + a1));
;     o[d0] = __builtin_amdgcn_mfma_scale_f32_32x32x64_f8f6f4(p8, vf, o[d0], 0, 0, 0, 127, 0, 127); }
; }
; __device__ __forceinline__ void qkt9(f32x16& p0, f32x16& p1, const char* Kn, const char* Kr, const v8i32* qf, const float init, int r32, int hi) {
; #pragma unroll
;   for (int r = 0; r < 16; ++r) { p0[r] = init; p1[r] = init; }
; #pragma unroll
;   for (int s = 0; s < 2; ++s) { const int c0 = s * 4 + hi * 2;
;     const v8i32 a0 = cat8(*reinterpret_cast<const v4i32*>(Kn + KN8SW(r32, c0)), *reinterpret_cast<const v4i32*>(Kn + KN8SW(r32, c0 + 1)));
;     const v8i32 a1 = cat8(*reinterpret_cast<const v4i32*>(Kn + 4096 + KN8SW(r32, c0)), *reinterpret_cast<const v4i32*>(Kn + 4096 + KN8SW(r32, c0 + 1)));
;     p0 = __builtin_amdgcn_mfma_scale_f32_32x32x64_f8f6f4(a0, qf[s], p0, 0, 0, 0, 127, 0, 124);
;     p1 = __builtin_amdgcn_mfma_scale_f32_32x32x64_f8f6f4(a1, qf[s], p1, 0, 0, 0, 127, 0, 124); }
;   { const int c0 = hi * 2;
.Lmla_s1_cont:
	ds_read_b128 v[114:117], v215 offset:16384
	ds_read_b128 v[118:121], v216 offset:16384
	ds_read_b128 v[222:225], v215 offset:20480
	ds_read_b128 v[226:229], v216 offset:20480
	s_waitcnt lgkmcnt(2)
	v_mfma_scale_f32_32x32x64_f8f6f4 v[114:129], v[114:121], v[146:153], v[230:245], v194, v193 op_sel_hi:[0,0,0]
	v_exp_f32_e32 v0, v82
	v_exp_f32_e32 v177, v83
	v_exp_f32_e32 v179, v84
	v_exp_f32_e32 v254, v85
	v_add_f32_e32 v219, v0, v177
	v_cvt_pk_fp8_f32 v246, v0, v177
	v_add_f32_e32 v219, v179, v219
	v_add_f32_e32 v219, v254, v219
	v_cvt_pk_fp8_f32 v246, v179, v254 op_sel:[0,0,1]
	v_exp_f32_e32 v0, v86
	v_exp_f32_e32 v177, v87
	v_exp_f32_e32 v179, v88
	v_exp_f32_e32 v254, v89
	v_add_f32_e32 v219, v0, v219
	v_add_f32_e32 v219, v177, v219
	v_cvt_pk_fp8_f32 v247, v0, v177
	v_add_f32_e32 v219, v179, v219
	v_add_f32_e32 v219, v254, v219
	v_cvt_pk_fp8_f32 v247, v179, v254 op_sel:[0,0,1]
	ds_read_b128 v[82:85], v213 offset:16384
	ds_read_b128 v[86:89], v214 offset:16384
	s_waitcnt lgkmcnt(2)
	v_mfma_scale_f32_32x32x64_f8f6f4 v[98:113], v[222:229], v[146:153], v[230:245], v194, v193 op_sel_hi:[0,0,0]
	ds_read_b128 v[222:225], v213 offset:20480
	ds_read_b128 v[226:229], v214 offset:20480
	v_exp_f32_e32 v0, v90
	v_exp_f32_e32 v177, v91
	v_exp_f32_e32 v179, v92
	v_exp_f32_e32 v254, v93
	v_add_f32_e32 v219, v0, v219
	v_add_f32_e32 v219, v177, v219
	v_cvt_pk_fp8_f32 v248, v0, v177
	v_add_f32_e32 v219, v179, v219
	v_add_f32_e32 v219, v254, v219
	v_cvt_pk_fp8_f32 v248, v179, v254 op_sel:[0,0,1]
	v_exp_f32_e32 v0, v94
	v_exp_f32_e32 v177, v95
	v_exp_f32_e32 v179, v96
	v_exp_f32_e32 v254, v97
	v_add_f32_e32 v219, v0, v219
	v_add_f32_e32 v219, v177, v219
	v_cvt_pk_fp8_f32 v249, v0, v177
	v_add_f32_e32 v219, v179, v219
	v_add_f32_e32 v219, v254, v219
	v_cvt_pk_fp8_f32 v249, v179, v254 op_sel:[0,0,1]
	ds_read_b128 v[90:93], v185 offset:32768
	ds_read_b128 v[94:97], v186 offset:32768
	s_waitcnt lgkmcnt(4)
	v_mfma_scale_f32_32x32x64_f8f6f4 v[114:129], v[82:89], v[138:145], v[114:129], v194, v193 op_sel_hi:[0,0,0]
	v_exp_f32_e32 v0, v66
	v_exp_f32_e32 v177, v67
	v_exp_f32_e32 v179, v68
	v_exp_f32_e32 v254, v69
	v_add_f32_e32 v219, v0, v219
	v_add_f32_e32 v219, v177, v219
	v_cvt_pk_fp8_f32 v250, v0, v177
	v_add_f32_e32 v219, v179, v219
	v_add_f32_e32 v219, v254, v219
	v_cvt_pk_fp8_f32 v250, v179, v254 op_sel:[0,0,1]
	s_waitcnt lgkmcnt(2)
	v_mfma_scale_f32_32x32x64_f8f6f4 v[98:113], v[222:229], v[138:145], v[98:113], v194, v193 op_sel_hi:[0,0,0]
	ds_read_b128 v[222:225], v185 offset:34816
	ds_read_b128 v[226:229], v186 offset:34816
	v_exp_f32_e32 v0, v70
	v_exp_f32_e32 v177, v71
	v_exp_f32_e32 v179, v72
	v_exp_f32_e32 v254, v73
	v_add_f32_e32 v219, v0, v219
	v_add_f32_e32 v219, v177, v219
	v_cvt_pk_fp8_f32 v251, v0, v177
	v_add_f32_e32 v219, v179, v219
	v_add_f32_e32 v219, v254, v219
	v_cvt_pk_fp8_f32 v251, v179, v254 op_sel:[0,0,1]
	v_exp_f32_e32 v0, v74
	v_exp_f32_e32 v177, v75
	v_exp_f32_e32 v179, v76
	v_exp_f32_e32 v254, v77
	v_add_f32_e32 v219, v0, v219
	v_add_f32_e32 v219, v177, v219
	v_cvt_pk_fp8_f32 v252, v0, v177
	v_add_f32_e32 v219, v179, v219
	v_add_f32_e32 v219, v254, v219
	v_cvt_pk_fp8_f32 v252, v179, v254 op_sel:[0,0,1]
	s_waitcnt lgkmcnt(2)
	v_mfma_scale_f32_32x32x64_f8f6f4 v[114:129], v[90:97], v[130:137], v[114:129], v194, v193 op_sel_hi:[0,0,0]
	v_exp_f32_e32 v0, v78
	v_exp_f32_e32 v177, v79
	v_exp_f32_e32 v179, v80
	v_exp_f32_e32 v254, v81
	v_add_f32_e32 v219, v0, v219
	v_add_f32_e32 v219, v177, v219
	v_cvt_pk_fp8_f32 v253, v0, v177
	v_add_f32_e32 v219, v179, v219
	v_add_f32_e32 v219, v254, v219
	v_cvt_pk_fp8_f32 v253, v179, v254 op_sel:[0,0,1]
	ds_read_b128 v[90:93], v185 offset:43008
	ds_read_b128 v[94:97], v186 offset:43008
	ds_read_b128 v[82:85], v185 offset:45056
	ds_read_b128 v[86:89], v186 offset:45056
	ds_read_b128 v[74:77], v185 offset:47104
	ds_read_b128 v[78:81], v186 offset:47104
	ds_read_b128 v[66:69], v185 offset:49152
	ds_read_b128 v[70:73], v186 offset:49152
	s_waitcnt lgkmcnt(8)
	v_mfma_scale_f32_32x32x64_f8f6f4 v[98:113], v[222:229], v[130:137], v[98:113], v194, v193 op_sel_hi:[0,0,0]
	v_mov_b32_e32 v0, v219
	s_nop 1
	v_permlane32_swap_b32_e32 v219, v0
	v_add_f32_e32 v219, v219, v0
	v_fma_f32 v209, v209, v218, v219
	v_max_f32_e32 v177, v114, v115
	v_max3_f32 v177, v177, v116, v117
	v_max3_f32 v177, v177, v118, v119
	v_max3_f32 v177, v177, v120, v121
	v_max3_f32 v177, v177, v122, v123
	v_max3_f32 v177, v177, v124, v125
	v_max3_f32 v177, v177, v126, v127
	v_max3_f32 v177, v177, v128, v129
	s_waitcnt lgkmcnt(6)
	v_mfma_scale_f32_32x32x64_f8f6f4 v[50:65], v[246:253], v[90:97], v[50:65], v194, v194 op_sel_hi:[0,0,0]
	s_waitcnt lgkmcnt(4)
	v_mfma_scale_f32_32x32x64_f8f6f4 v[34:49], v[246:253], v[82:89], v[34:49], v194, v194 op_sel_hi:[0,0,0]
	s_waitcnt vmcnt(0)
	s_waitcnt lgkmcnt(0)
	s_barrier
	v_max_f32_e32 v0, v98, v99
	v_max3_f32 v0, v0, v100, v101
	v_max3_f32 v0, v0, v102, v103
	v_max3_f32 v0, v0, v104, v105
	s_waitcnt lgkmcnt(2)
	v_mfma_scale_f32_32x32x64_f8f6f4 v[18:33], v[246:253], v[74:81], v[18:33], v194, v194 op_sel_hi:[0,0,0]
	s_add_i32 m0, s98, 0xa800
	s_nop 0
	global_load_lds_dwordx4 v176, s[18:19]
	s_add_i32 m0, s98, 0xc800
	s_nop 0
	global_load_lds_dwordx4 v178, s[16:17]
	v_add_u32_e32 v176, 0x2000, v176
	v_add_u32_e32 v178, 0x20000, v178
	v_max3_f32 v0, v0, v106, v107
	v_max3_f32 v0, v0, v108, v109
	v_max3_f32 v0, v0, v110, v111
	v_max3_f32 v0, v0, v112, v113
	s_waitcnt lgkmcnt(0)
	v_mfma_scale_f32_32x32x64_f8f6f4 v[2:17], v[246:253], v[66:73], v[2:17], v194, v194 op_sel_hi:[0,0,0]
	v_max_f32_e32 v177, v177, v0
	v_mov_b32_e32 v0, v177
	v_mov_b32_e32 v221, 1.0
	s_nop 0
	v_permlane32_swap_b32_e32 v177, v0
	v_max_f32_e32 v177, v177, v0
	v_cmp_ge_f32_e32 vcc, s90, v177
	s_cmp_eq_u64 vcc, exec
	s_cbranch_scc0 .Lmla_s2_newmax
; __device__ __forceinline__ void finishSM9(f32x16& p0, f32x16& p1, float alpha, float& l_reg, v8i32& p8) {
; #pragma unroll
;   for (int r = 0; r < 16; ++r) { p0[r] = __builtin_amdgcn_exp2f(p0[r]); p1[r] = __builtin_amdgcn_exp2f(p1[r]); }
;   float ps = 0;
; #pragma unroll
;   for (int r = 0; r < 16; ++r) ps += p0[r];
; #pragma unroll
;   for (int r = 0; r < 16; ++r) ps += p1[r];
;   { auto rr = __builtin_amdgcn_permlane32_swap(__float_as_uint(ps), __float_as_uint(ps), false, false);
;     ps = __uint_as_float(rr[0]) + __uint_as_float(rr[1]); }
;   l_reg = l_reg * alpha + ps;
; #pragma unroll
;   for (int g = 0; g < 4; ++g) {
;     int w = __builtin_amdgcn_cvt_pk_fp8_f32(p0[4 * g], p0[4 * g + 1], 0, false); p8[g] = __builtin_amdgcn_cvt_pk_fp8_f32(p0[4 * g + 2], p0[4 * g + 3], w, true);
;     int u = __builtin_amdgcn_cvt_pk_fp8_f32(p1[4 * g], p1[4 * g + 1], 0, false); p8[4 + g] = __builtin_amdgcn_cvt_pk_fp8_f32(p1[4 * g + 2], p1[4 * g + 3], u, true); }
; }
; __device__ __forceinline__ void pv8(f32x16* o, const char* Vt, const v8i32 p8, int r32, int hi) {
;   const int sw = (r32 >> 2) & 3, a0 = r32 * 64 + (((hi * 2) ^ sw) << 4), a1 = r32 * 64 + (((hi * 2 + 1) ^ sw) << 4);
; #pragma unroll
;   for (int d0 = 0; d0 < 4; ++d0) {
;     const v8i32 vf = cat8(*reinterpret_cast<const v4i32*>(Vt + d0 * 2048 + a0), *reinterpret_cast<const v4i32*>(Vt + d0 * 2048 + a1));
;     o[d0] = __builtin_amdgcn_mfma_scale_f32_32x32x64_f8f6f4(p8, vf, o[d0], 0, 0, 0, 127, 0, 127); }
; }
; __device__ __forceinline__ void qkt9(f32x16& p0, f32x16& p1, const char* Kn, const char* Kr, const v8i32* qf, const float init, int r32, int hi) {
; #pragma unroll
;   for (int r = 0; r < 16; ++r) { p0[r] = init; p1[r] = init; }
; #pragma unroll
;   for (int s = 0; s < 2; ++s) { const int c0 = s * 4 + hi * 2;
;     const v8i32 a0 = cat8(*reinterpret_cast<const v4i32*>(Kn + KN8SW(r32, c0)), *reinterpret_cast<const v4i32*>(Kn + KN8SW(r32, c0 + 1)));
;     const v8i32 a1 = cat8(*reinterpret_cast<const v4i32*>(Kn + 4096 + KN8SW(r32, c0)), *reinterpret_cast<const v4i32*>(Kn + 4096 + KN8SW(r32, c0 + 1)));
;     p0 = __builtin_amdgcn_mfma_scale_f32_32x32x64_f8f6f4(a0, qf[s], p0, 0, 0, 0, 127, 0, 124);
;     p1 = __builtin_amdgcn_mfma_scale_f32_32x32x64_f8f6f4(a1, qf[s], p1, 0, 0, 0, 127, 0, 124); }
;   { const int c0 = hi * 2;
.Lmla_s2_cont:
	ds_read_b128 v[82:85], v215 offset:24576
	ds_read_b128 v[86:89], v216 offset:24576
	ds_read_b128 v[222:225], v215 offset:28672
	ds_read_b128 v[226:229], v216 offset:28672
	s_waitcnt lgkmcnt(2)
	v_mfma_scale_f32_32x32x64_f8f6f4 v[82:97], v[82:89], v[146:153], v[230:245], v194, v193 op_sel_hi:[0,0,0]
	v_exp_f32_e32 v0, v114
	v_exp_f32_e32 v177, v115
	v_exp_f32_e32 v179, v116
	v_exp_f32_e32 v254, v117
	v_add_f32_e32 v219, v0, v177
	v_cvt_pk_fp8_f32 v246, v0, v177
	v_add_f32_e32 v219, v179, v219
	v_add_f32_e32 v219, v254, v219
	v_cvt_pk_fp8_f32 v246, v179, v254 op_sel:[0,0,1]
	v_exp_f32_e32 v0, v118
	v_exp_f32_e32 v177, v119
	v_exp_f32_e32 v179, v120
	v_exp_f32_e32 v254, v121
	v_add_f32_e32 v219, v0, v219
	v_add_f32_e32 v219, v177, v219
	v_cvt_pk_fp8_f32 v247, v0, v177
	v_add_f32_e32 v219, v179, v219
	v_add_f32_e32 v219, v254, v219
	v_cvt_pk_fp8_f32 v247, v179, v254 op_sel:[0,0,1]
	ds_read_b128 v[114:117], v213 offset:24576
	ds_read_b128 v[118:121], v214 offset:24576
	s_waitcnt lgkmcnt(2)
	v_mfma_scale_f32_32x32x64_f8f6f4 v[66:81], v[222:229], v[146:153], v[230:245], v194, v193 op_sel_hi:[0,0,0]
	ds_read_b128 v[222:225], v213 offset:28672
	ds_read_b128 v[226:229], v214 offset:28672
	v_exp_f32_e32 v0, v122
	v_exp_f32_e32 v177, v123
	v_exp_f32_e32 v179, v124
	v_exp_f32_e32 v254, v125
	v_add_f32_e32 v219, v0, v219
	v_add_f32_e32 v219, v177, v219
	v_cvt_pk_fp8_f32 v248, v0, v177
	v_add_f32_e32 v219, v179, v219
	v_add_f32_e32 v219, v254, v219
	v_cvt_pk_fp8_f32 v248, v179, v254 op_sel:[0,0,1]
	v_exp_f32_e32 v0, v126
	v_exp_f32_e32 v177, v127
	v_exp_f32_e32 v179, v128
	v_exp_f32_e32 v254, v129
	v_add_f32_e32 v219, v0, v219
	v_add_f32_e32 v219, v177, v219
	v_cvt_pk_fp8_f32 v249, v0, v177
	v_add_f32_e32 v219, v179, v219
	v_add_f32_e32 v219, v254, v219
	v_cvt_pk_fp8_f32 v249, v179, v254 op_sel:[0,0,1]
	ds_read_b128 v[122:125], v185 offset:36864
	ds_read_b128 v[126:129], v186 offset:36864
	s_waitcnt lgkmcnt(4)
	v_mfma_scale_f32_32x32x64_f8f6f4 v[82:97], v[114:121], v[138:145], v[82:97], v194, v193 op_sel_hi:[0,0,0]
	v_exp_f32_e32 v0, v98
	v_exp_f32_e32 v177, v99
	v_exp_f32_e32 v179, v100
	v_exp_f32_e32 v254, v101
	v_add_f32_e32 v219, v0, v219
	v_add_f32_e32 v219, v177, v219
	v_cvt_pk_fp8_f32 v250, v0, v177
	v_add_f32_e32 v219, v179, v219
	v_add_f32_e32 v219, v254, v219
	v_cvt_pk_fp8_f32 v250, v179, v254 op_sel:[0,0,1]
	s_waitcnt lgkmcnt(2)
	v_mfma_scale_f32_32x32x64_f8f6f4 v[66:81], v[222:229], v[138:145], v[66:81], v194, v193 op_sel_hi:[0,0,0]
	ds_read_b128 v[222:225], v185 offset:38912
	ds_read_b128 v[226:229], v186 offset:38912
	v_exp_f32_e32 v0, v102
	v_exp_f32_e32 v177, v103
	v_exp_f32_e32 v179, v104
	v_exp_f32_e32 v254, v105
	v_add_f32_e32 v219, v0, v219
	v_add_f32_e32 v219, v177, v219
	v_cvt_pk_fp8_f32 v251, v0, v177
	v_add_f32_e32 v219, v179, v219
	v_add_f32_e32 v219, v254, v219
	v_cvt_pk_fp8_f32 v251, v179, v254 op_sel:[0,0,1]
	v_exp_f32_e32 v0, v106
	v_exp_f32_e32 v177, v107
	v_exp_f32_e32 v179, v108
	v_exp_f32_e32 v254, v109
	v_add_f32_e32 v219, v0, v219
	v_add_f32_e32 v219, v177, v219
	v_cvt_pk_fp8_f32 v252, v0, v177
	v_add_f32_e32 v219, v179, v219
	v_add_f32_e32 v219, v254, v219
	v_cvt_pk_fp8_f32 v252, v179, v254 op_sel:[0,0,1]
	s_waitcnt lgkmcnt(2)
	v_mfma_scale_f32_32x32x64_f8f6f4 v[82:97], v[122:129], v[130:137], v[82:97], v194, v193 op_sel_hi:[0,0,0]
	v_exp_f32_e32 v0, v110
	v_exp_f32_e32 v177, v111
	v_exp_f32_e32 v179, v112
	v_exp_f32_e32 v254, v113
	v_add_f32_e32 v219, v0, v219
	v_add_f32_e32 v219, v177, v219
	v_cvt_pk_fp8_f32 v253, v0, v177
	v_add_f32_e32 v219, v179, v219
	v_add_f32_e32 v219, v254, v219
	v_cvt_pk_fp8_f32 v253, v179, v254 op_sel:[0,0,1]
	ds_read_b128 v[122:125], v185 offset:0
	ds_read_b128 v[126:129], v186 offset:0
	ds_read_b128 v[114:117], v185 offset:2048
	ds_read_b128 v[118:121], v186 offset:2048
	ds_read_b128 v[106:109], v185 offset:4096
	ds_read_b128 v[110:113], v186 offset:4096
	ds_read_b128 v[98:101], v185 offset:6144
	ds_read_b128 v[102:105], v186 offset:6144
	s_waitcnt lgkmcnt(8)
	v_mfma_scale_f32_32x32x64_f8f6f4 v[66:81], v[222:229], v[130:137], v[66:81], v194, v193 op_sel_hi:[0,0,0]
	v_mov_b32_e32 v0, v219
	s_nop 1
	v_permlane32_swap_b32_e32 v219, v0
	v_add_f32_e32 v219, v219, v0
	v_fma_f32 v209, v209, v221, v219
	v_max_f32_e32 v177, v82, v83
	v_max3_f32 v177, v177, v84, v85
	v_max3_f32 v177, v177, v86, v87
	v_max3_f32 v177, v177, v88, v89
	v_max3_f32 v177, v177, v90, v91
	v_max3_f32 v177, v177, v92, v93
	v_max3_f32 v177, v177, v94, v95
	v_max3_f32 v177, v177, v96, v97
	s_waitcnt lgkmcnt(6)
	v_mfma_scale_f32_32x32x64_f8f6f4 v[50:65], v[246:253], v[122:129], v[50:65], v194, v194 op_sel_hi:[0,0,0]
	s_waitcnt lgkmcnt(4)
	v_mfma_scale_f32_32x32x64_f8f6f4 v[34:49], v[246:253], v[114:121], v[34:49], v194, v194 op_sel_hi:[0,0,0]
	s_waitcnt vmcnt(0)
	s_waitcnt lgkmcnt(0)
	s_barrier
	v_max_f32_e32 v0, v66, v67
	v_max3_f32 v0, v0, v68, v69
	v_max3_f32 v0, v0, v70, v71
	v_max3_f32 v0, v0, v72, v73
	s_waitcnt lgkmcnt(2)
	v_mfma_scale_f32_32x32x64_f8f6f4 v[18:33], v[246:253], v[106:113], v[18:33], v194, v194 op_sel_hi:[0,0,0]
	s_add_i32 m0, s98, 0x0
	s_nop 0
	global_load_lds_dwordx4 v176, s[18:19]
	s_add_i32 m0, s98, 0x4000
	s_nop 0
	global_load_lds_dwordx4 v178, s[16:17]
	v_add_u32_e32 v176, 0x2000, v176
	v_add_u32_e32 v178, 0x20000, v178
	v_max3_f32 v0, v0, v74, v75
	v_max3_f32 v0, v0, v76, v77
	v_max3_f32 v0, v0, v78, v79
	v_max3_f32 v0, v0, v80, v81
	s_waitcnt lgkmcnt(0)
	v_mfma_scale_f32_32x32x64_f8f6f4 v[2:17], v[246:253], v[98:105], v[2:17], v194, v194 op_sel_hi:[0,0,0]
	v_max_f32_e32 v177, v177, v0
	v_mov_b32_e32 v0, v177
	v_mov_b32_e32 v218, 1.0
	s_nop 0
	v_permlane32_swap_b32_e32 v177, v0
	v_max_f32_e32 v177, v177, v0
	v_cmp_ge_f32_e32 vcc, s90, v177
	s_cmp_eq_u64 vcc, exec
	s_cbranch_scc0 .Lmla_s3_newmax
; __device__ __forceinline__ void finishSM9(f32x16& p0, f32x16& p1, float alpha, float& l_reg, v8i32& p8) {
; #pragma unroll
;   for (int r = 0; r < 16; ++r) { p0[r] = __builtin_amdgcn_exp2f(p0[r]); p1[r] = __builtin_amdgcn_exp2f(p1[r]); }
;   float ps = 0;
; #pragma unroll
;   for (int r = 0; r < 16; ++r) ps += p0[r];
; #pragma unroll
;   for (int r = 0; r < 16; ++r) ps += p1[r];
;   { auto rr = __builtin_amdgcn_permlane32_swap(__float_as_uint(ps), __float_as_uint(ps), false, false);
;     ps = __uint_as_float(rr[0]) + __uint_as_float(rr[1]); }
;   l_reg = l_reg * alpha + ps;
; #pragma unroll
;   for (int g = 0; g < 4; ++g) {
;     int w = __builtin_amdgcn_cvt_pk_fp8_f32(p0[4 * g], p0[4 * g + 1], 0, false); p8[g] = __builtin_amdgcn_cvt_pk_fp8_f32(p0[4 * g + 2], p0[4 * g + 3], w, true);
;     int u = __builtin_amdgcn_cvt_pk_fp8_f32(p1[4 * g], p1[4 * g + 1], 0, false); p8[4 + g] = __builtin_amdgcn_cvt_pk_fp8_f32(p1[4 * g + 2], p1[4 * g + 3], u, true); }
; }
; __device__ __forceinline__ void pv8(f32x16* o, const char* Vt, const v8i32 p8, int r32, int hi) {
;   const int sw = (r32 >> 2) & 3, a0 = r32 * 64 + (((hi * 2) ^ sw) << 4), a1 = r32 * 64 + (((hi * 2 + 1) ^ sw) << 4);
; #pragma unroll
;   for (int d0 = 0; d0 < 4; ++d0) {
;     const v8i32 vf = cat8(*reinterpret_cast<const v4i32*>(Vt + d0 * 2048 + a0), *reinterpret_cast<const v4i32*>(Vt + d0 * 2048 + a1));
;     o[d0] = __builtin_amdgcn_mfma_scale_f32_32x32x64_f8f6f4(p8, vf, o[d0], 0, 0, 0, 127, 0, 127); }
; }
; __device__ __forceinline__ void qkt9(f32x16& p0, f32x16& p1, const char* Kn, const char* Kr, const v8i32* qf, const float init, int r32, int hi) {
; #pragma unroll
;   for (int r = 0; r < 16; ++r) { p0[r] = init; p1[r] = init; }
; #pragma unroll
;   for (int s = 0; s < 2; ++s) { const int c0 = s * 4 + hi * 2;
;     const v8i32 a0 = cat8(*reinterpret_cast<const v4i32*>(Kn + KN8SW(r32, c0)), *reinterpret_cast<const v4i32*>(Kn + KN8SW(r32, c0 + 1)));
;     const v8i32 a1 = cat8(*reinterpret_cast<const v4i32*>(Kn + 4096 + KN8SW(r32, c0)), *reinterpret_cast<const v4i32*>(Kn + 4096 + KN8SW(r32, c0 + 1)));
;     p0 = __builtin_amdgcn_mfma_scale_f32_32x32x64_f8f6f4(a0, qf[s], p0, 0, 0, 0, 127, 0, 124);
;     p1 = __builtin_amdgcn_mfma_scale_f32_32x32x64_f8f6f4(a1, qf[s], p1, 0, 0, 0, 127, 0, 124); }
;   { const int c0 = hi * 2;
.Lmla_s3_cont:
	ds_read_b128 v[114:117], v215 offset:51200
	ds_read_b128 v[118:121], v216 offset:51200
	ds_read_b128 v[222:225], v215 offset:55296
	ds_read_b128 v[226:229], v216 offset:55296
	s_waitcnt lgkmcnt(2)
	v_mfma_scale_f32_32x32x64_f8f6f4 v[114:129], v[114:121], v[146:153], v[230:245], v194, v193 op_sel_hi:[0,0,0]
	v_exp_f32_e32 v0, v82
	v_exp_f32_e32 v177, v83
	v_exp_f32_e32 v179, v84
	v_exp_f32_e32 v254, v85
	v_add_f32_e32 v219, v0, v177
	v_cvt_pk_fp8_f32 v246, v0, v177
	v_add_f32_e32 v219, v179, v219
	v_add_f32_e32 v219, v254, v219
	v_cvt_pk_fp8_f32 v246, v179, v254 op_sel:[0,0,1]
	v_exp_f32_e32 v0, v86
	v_exp_f32_e32 v177, v87
	v_exp_f32_e32 v179, v88
	v_exp_f32_e32 v254, v89
	v_add_f32_e32 v219, v0, v219
	v_add_f32_e32 v219, v177, v219
	v_cvt_pk_fp8_f32 v247, v0, v177
	v_add_f32_e32 v219, v179, v219
	v_add_f32_e32 v219, v254, v219
	v_cvt_pk_fp8_f32 v247, v179, v254 op_sel:[0,0,1]
	ds_read_b128 v[82:85], v213 offset:51200
	ds_read_b128 v[86:89], v214 offset:51200
	s_waitcnt lgkmcnt(2)
	v_mfma_scale_f32_32x32x64_f8f6f4 v[98:113], v[222:229], v[146:153], v[230:245], v194, v193 op_sel_hi:[0,0,0]
	ds_read_b128 v[222:225], v213 offset:55296
	ds_read_b128 v[226:229], v214 offset:55296
	v_exp_f32_e32 v0, v90
	v_exp_f32_e32 v177, v91
	v_exp_f32_e32 v179, v92
	v_exp_f32_e32 v254, v93
	v_add_f32_e32 v219, v0, v219
	v_add_f32_e32 v219, v177, v219
	v_cvt_pk_fp8_f32 v248, v0, v177
	v_add_f32_e32 v219, v179, v219
	v_add_f32_e32 v219, v254, v219
	v_cvt_pk_fp8_f32 v248, v179, v254 op_sel:[0,0,1]
	v_exp_f32_e32 v0, v94
	v_exp_f32_e32 v177, v95
	v_exp_f32_e32 v179, v96
	v_exp_f32_e32 v254, v97
	v_add_f32_e32 v219, v0, v219
	v_add_f32_e32 v219, v177, v219
	v_cvt_pk_fp8_f32 v249, v0, v177
	v_add_f32_e32 v219, v179, v219
	v_add_f32_e32 v219, v254, v219
	v_cvt_pk_fp8_f32 v249, v179, v254 op_sel:[0,0,1]
	ds_read_b128 v[90:93], v185 offset:59392
	ds_read_b128 v[94:97], v186 offset:59392
	s_waitcnt lgkmcnt(4)
	v_mfma_scale_f32_32x32x64_f8f6f4 v[114:129], v[82:89], v[138:145], v[114:129], v194, v193 op_sel_hi:[0,0,0]
	v_exp_f32_e32 v0, v66
	v_exp_f32_e32 v177, v67
	v_exp_f32_e32 v179, v68
	v_exp_f32_e32 v254, v69
	v_add_f32_e32 v219, v0, v219
	v_add_f32_e32 v219, v177, v219
	v_cvt_pk_fp8_f32 v250, v0, v177
	v_add_f32_e32 v219, v179, v219
	v_add_f32_e32 v219, v254, v219
	v_cvt_pk_fp8_f32 v250, v179, v254 op_sel:[0,0,1]
	s_waitcnt lgkmcnt(2)
	v_mfma_scale_f32_32x32x64_f8f6f4 v[98:113], v[222:229], v[138:145], v[98:113], v194, v193 op_sel_hi:[0,0,0]
	ds_read_b128 v[222:225], v185 offset:61440
	ds_read_b128 v[226:229], v186 offset:61440
	v_exp_f32_e32 v0, v70
	v_exp_f32_e32 v177, v71
	v_exp_f32_e32 v179, v72
	v_exp_f32_e32 v254, v73
	v_add_f32_e32 v219, v0, v219
	v_add_f32_e32 v219, v177, v219
	v_cvt_pk_fp8_f32 v251, v0, v177
	v_add_f32_e32 v219, v179, v219
	v_add_f32_e32 v219, v254, v219
	v_cvt_pk_fp8_f32 v251, v179, v254 op_sel:[0,0,1]
	v_exp_f32_e32 v0, v74
	v_exp_f32_e32 v177, v75
	v_exp_f32_e32 v179, v76
	v_exp_f32_e32 v254, v77
	v_add_f32_e32 v219, v0, v219
	v_add_f32_e32 v219, v177, v219
	v_cvt_pk_fp8_f32 v252, v0, v177
	v_add_f32_e32 v219, v179, v219
	v_add_f32_e32 v219, v254, v219
	v_cvt_pk_fp8_f32 v252, v179, v254 op_sel:[0,0,1]
	s_waitcnt lgkmcnt(2)
	v_mfma_scale_f32_32x32x64_f8f6f4 v[114:129], v[90:97], v[130:137], v[114:129], v194, v193 op_sel_hi:[0,0,0]
	v_exp_f32_e32 v0, v78
	v_exp_f32_e32 v177, v79
	v_exp_f32_e32 v179, v80
	v_exp_f32_e32 v254, v81
	v_add_f32_e32 v219, v0, v219
	v_add_f32_e32 v219, v177, v219
	v_cvt_pk_fp8_f32 v253, v0, v177
	v_add_f32_e32 v219, v179, v219
	v_add_f32_e32 v219, v254, v219
	v_cvt_pk_fp8_f32 v253, v179, v254 op_sel:[0,0,1]
	ds_read_b128 v[90:93], v185 offset:8192
	ds_read_b128 v[94:97], v186 offset:8192
	ds_read_b128 v[82:85], v185 offset:10240
	ds_read_b128 v[86:89], v186 offset:10240
	ds_read_b128 v[74:77], v185 offset:12288
	ds_read_b128 v[78:81], v186 offset:12288
	ds_read_b128 v[66:69], v185 offset:14336
	ds_read_b128 v[70:73], v186 offset:14336
	s_waitcnt lgkmcnt(8)
	v_mfma_scale_f32_32x32x64_f8f6f4 v[98:113], v[222:229], v[130:137], v[98:113], v194, v193 op_sel_hi:[0,0,0]
	v_mov_b32_e32 v0, v219
	s_nop 1
	v_permlane32_swap_b32_e32 v219, v0
	v_add_f32_e32 v219, v219, v0
	v_fma_f32 v209, v209, v218, v219
	v_max_f32_e32 v177, v114, v115
	v_max3_f32 v177, v177, v116, v117
	v_max3_f32 v177, v177, v118, v119
	v_max3_f32 v177, v177, v120, v121
	v_max3_f32 v177, v177, v122, v123
	v_max3_f32 v177, v177, v124, v125
	v_max3_f32 v177, v177, v126, v127
	v_max3_f32 v177, v177, v128, v129
	s_waitcnt lgkmcnt(6)
	v_mfma_scale_f32_32x32x64_f8f6f4 v[50:65], v[246:253], v[90:97], v[50:65], v194, v194 op_sel_hi:[0,0,0]
	s_waitcnt lgkmcnt(4)
	v_mfma_scale_f32_32x32x64_f8f6f4 v[34:49], v[246:253], v[82:89], v[34:49], v194, v194 op_sel_hi:[0,0,0]
	s_waitcnt vmcnt(0)
	s_waitcnt lgkmcnt(0)
	s_barrier
	v_max_f32_e32 v0, v98, v99
	v_max3_f32 v0, v0, v100, v101
	v_max3_f32 v0, v0, v102, v103
	v_max3_f32 v0, v0, v104, v105
	s_waitcnt lgkmcnt(2)
	v_mfma_scale_f32_32x32x64_f8f6f4 v[18:33], v[246:253], v[74:81], v[18:33], v194, v194 op_sel_hi:[0,0,0]
	s_add_i32 m0, s98, 0x2000
	s_nop 0
	global_load_lds_dwordx4 v176, s[18:19]
	s_add_i32 m0, s98, 0x6000
	s_nop 0
	global_load_lds_dwordx4 v178, s[16:17]
	v_add_u32_e32 v176, 0x2000, v176
	v_add_u32_e32 v178, 0x20000, v178
	v_max3_f32 v0, v0, v106, v107
	v_max3_f32 v0, v0, v108, v109
	v_max3_f32 v0, v0, v110, v111
	v_max3_f32 v0, v0, v112, v113
	s_waitcnt lgkmcnt(0)
	v_mfma_scale_f32_32x32x64_f8f6f4 v[2:17], v[246:253], v[66:73], v[2:17], v194, v194 op_sel_hi:[0,0,0]
	v_max_f32_e32 v177, v177, v0
	v_mov_b32_e32 v0, v177
	v_mov_b32_e32 v221, 1.0
	s_nop 0
	v_permlane32_swap_b32_e32 v177, v0
	v_max_f32_e32 v177, v177, v0
	v_cmp_ge_f32_e32 vcc, s90, v177
	s_cmp_eq_u64 vcc, exec
	s_cbranch_scc0 .Lmla_s4_newmax
; __device__ __forceinline__ void finishSM9(f32x16& p0, f32x16& p1, float alpha, float& l_reg, v8i32& p8) {
; #pragma unroll
;   for (int r = 0; r < 16; ++r) { p0[r] = __builtin_amdgcn_exp2f(p0[r]); p1[r] = __builtin_amdgcn_exp2f(p1[r]); }
;   float ps = 0;
; #pragma unroll
;   for (int r = 0; r < 16; ++r) ps += p0[r];
; #pragma unroll
;   for (int r = 0; r < 16; ++r) ps += p1[r];
;   { auto rr = __builtin_amdgcn_permlane32_swap(__float_as_uint(ps), __float_as_uint(ps), false, false);
;     ps = __uint_as_float(rr[0]) + __uint_as_float(rr[1]); }
;   l_reg = l_reg * alpha + ps;
; #pragma unroll
;   for (int g = 0; g < 4; ++g) {
;     int w = __builtin_amdgcn_cvt_pk_fp8_f32(p0[4 * g], p0[4 * g + 1], 0, false); p8[g] = __builtin_amdgcn_cvt_pk_fp8_f32(p0[4 * g + 2], p0[4 * g + 3], w, true);
;     int u = __builtin_amdgcn_cvt_pk_fp8_f32(p1[4 * g], p1[4 * g + 1], 0, false); p8[4 + g] = __builtin_amdgcn_cvt_pk_fp8_f32(p1[4 * g + 2], p1[4 * g + 3], u, true); }
; }
; __device__ __forceinline__ void pv8(f32x16* o, const char* Vt, const v8i32 p8, int r32, int hi) {
;   const int sw = (r32 >> 2) & 3, a0 = r32 * 64 + (((hi * 2) ^ sw) << 4), a1 = r32 * 64 + (((hi * 2 + 1) ^ sw) << 4);
; #pragma unroll
;   for (int d0 = 0; d0 < 4; ++d0) {
;     const v8i32 vf = cat8(*reinterpret_cast<const v4i32*>(Vt + d0 * 2048 + a0), *reinterpret_cast<const v4i32*>(Vt + d0 * 2048 + a1));
;     o[d0] = __builtin_amdgcn_mfma_scale_f32_32x32x64_f8f6f4(p8, vf, o[d0], 0, 0, 0, 127, 0, 127); }
; }
; __device__ __forceinline__ void qkt9(f32x16& p0, f32x16& p1, const char* Kn, const char* Kr, const v8i32* qf, const float init, int r32, int hi) {
; #pragma unroll
;   for (int r = 0; r < 16; ++r) { p0[r] = init; p1[r] = init; }
; #pragma unroll
;   for (int s = 0; s < 2; ++s) { const int c0 = s * 4 + hi * 2;
;     const v8i32 a0 = cat8(*reinterpret_cast<const v4i32*>(Kn + KN8SW(r32, c0)), *reinterpret_cast<const v4i32*>(Kn + KN8SW(r32, c0 + 1)));
;     const v8i32 a1 = cat8(*reinterpret_cast<const v4i32*>(Kn + 4096 + KN8SW(r32, c0)), *reinterpret_cast<const v4i32*>(Kn + 4096 + KN8SW(r32, c0 + 1)));
;     p0 = __builtin_amdgcn_mfma_scale_f32_32x32x64_f8f6f4(a0, qf[s], p0, 0, 0, 0, 127, 0, 124);
;     p1 = __builtin_amdgcn_mfma_scale_f32_32x32x64_f8f6f4(a1, qf[s], p1, 0, 0, 0, 127, 0, 124); }
;   { const int c0 = hi * 2;
.Lmla_s4_cont:
	ds_read_b128 v[82:85], v215 offset:16384
	ds_read_b128 v[86:89], v216 offset:16384
	ds_read_b128 v[222:225], v215 offset:20480
	ds_read_b128 v[226:229], v216 offset:20480
	s_waitcnt lgkmcnt(2)
	v_mfma_scale_f32_32x32x64_f8f6f4 v[82:97], v[82:89], v[146:153], v[230:245], v194, v193 op_sel_hi:[0,0,0]
	v_exp_f32_e32 v0, v114
	v_exp_f32_e32 v177, v115
	v_exp_f32_e32 v179, v116
	v_exp_f32_e32 v254, v117
	v_add_f32_e32 v219, v0, v177
	v_cvt_pk_fp8_f32 v246, v0, v177
	v_add_f32_e32 v219, v179, v219
	v_add_f32_e32 v219, v254, v219
	v_cvt_pk_fp8_f32 v246, v179, v254 op_sel:[0,0,1]
	v_exp_f32_e32 v0, v118
	v_exp_f32_e32 v177, v119
	v_exp_f32_e32 v179, v120
	v_exp_f32_e32 v254, v121
	v_add_f32_e32 v219, v0, v219
	v_add_f32_e32 v219, v177, v219
	v_cvt_pk_fp8_f32 v247, v0, v177
	v_add_f32_e32 v219, v179, v219
	v_add_f32_e32 v219, v254, v219
	v_cvt_pk_fp8_f32 v247, v179, v254 op_sel:[0,0,1]
	ds_read_b128 v[114:117], v213 offset:16384
	ds_read_b128 v[118:121], v214 offset:16384
	s_waitcnt lgkmcnt(2)
	v_mfma_scale_f32_32x32x64_f8f6f4 v[66:81], v[222:229], v[146:153], v[230:245], v194, v193 op_sel_hi:[0,0,0]
	ds_read_b128 v[222:225], v213 offset:20480
	ds_read_b128 v[226:229], v214 offset:20480
	v_exp_f32_e32 v0, v122
	v_exp_f32_e32 v177, v123
	v_exp_f32_e32 v179, v124
	v_exp_f32_e32 v254, v125
	v_add_f32_e32 v219, v0, v219
	v_add_f32_e32 v219, v177, v219
	v_cvt_pk_fp8_f32 v248, v0, v177
	v_add_f32_e32 v219, v179, v219
	v_add_f32_e32 v219, v254, v219
	v_cvt_pk_fp8_f32 v248, v179, v254 op_sel:[0,0,1]
	v_exp_f32_e32 v0, v126
	v_exp_f32_e32 v177, v127
	v_exp_f32_e32 v179, v128
	v_exp_f32_e32 v254, v129
	v_add_f32_e32 v219, v0, v219
	v_add_f32_e32 v219, v177, v219
	v_cvt_pk_fp8_f32 v249, v0, v177
	v_add_f32_e32 v219, v179, v219
	v_add_f32_e32 v219, v254, v219
	v_cvt_pk_fp8_f32 v249, v179, v254 op_sel:[0,0,1]
	ds_read_b128 v[122:125], v185 offset:32768
	ds_read_b128 v[126:129], v186 offset:32768
	s_waitcnt lgkmcnt(4)
	v_mfma_scale_f32_32x32x64_f8f6f4 v[82:97], v[114:121], v[138:145], v[82:97], v194, v193 op_sel_hi:[0,0,0]
	v_exp_f32_e32 v0, v98
	v_exp_f32_e32 v177, v99
	v_exp_f32_e32 v179, v100
	v_exp_f32_e32 v254, v101
	v_add_f32_e32 v219, v0, v219
	v_add_f32_e32 v219, v177, v219
	v_cvt_pk_fp8_f32 v250, v0, v177
	v_add_f32_e32 v219, v179, v219
	v_add_f32_e32 v219, v254, v219
	v_cvt_pk_fp8_f32 v250, v179, v254 op_sel:[0,0,1]
	s_waitcnt lgkmcnt(2)
	v_mfma_scale_f32_32x32x64_f8f6f4 v[66:81], v[222:229], v[138:145], v[66:81], v194, v193 op_sel_hi:[0,0,0]
	ds_read_b128 v[222:225], v185 offset:34816
	ds_read_b128 v[226:229], v186 offset:34816
	v_exp_f32_e32 v0, v102
	v_exp_f32_e32 v177, v103
	v_exp_f32_e32 v179, v104
	v_exp_f32_e32 v254, v105
	v_add_f32_e32 v219, v0, v219
	v_add_f32_e32 v219, v177, v219
	v_cvt_pk_fp8_f32 v251, v0, v177
	v_add_f32_e32 v219, v179, v219
	v_add_f32_e32 v219, v254, v219
	v_cvt_pk_fp8_f32 v251, v179, v254 op_sel:[0,0,1]
	v_exp_f32_e32 v0, v106
	v_exp_f32_e32 v177, v107
	v_exp_f32_e32 v179, v108
	v_exp_f32_e32 v254, v109
	v_add_f32_e32 v219, v0, v219
	v_add_f32_e32 v219, v177, v219
	v_cvt_pk_fp8_f32 v252, v0, v177
	v_add_f32_e32 v219, v179, v219
	v_add_f32_e32 v219, v254, v219
	v_cvt_pk_fp8_f32 v252, v179, v254 op_sel:[0,0,1]
	s_waitcnt lgkmcnt(2)
	v_mfma_scale_f32_32x32x64_f8f6f4 v[82:97], v[122:129], v[130:137], v[82:97], v194, v193 op_sel_hi:[0,0,0]
	v_exp_f32_e32 v0, v110
	v_exp_f32_e32 v177, v111
	v_exp_f32_e32 v179, v112
	v_exp_f32_e32 v254, v113
	v_add_f32_e32 v219, v0, v219
	v_add_f32_e32 v219, v177, v219
	v_cvt_pk_fp8_f32 v253, v0, v177
	v_add_f32_e32 v219, v179, v219
	v_add_f32_e32 v219, v254, v219
	v_cvt_pk_fp8_f32 v253, v179, v254 op_sel:[0,0,1]
	ds_read_b128 v[122:125], v185 offset:43008
	ds_read_b128 v[126:129], v186 offset:43008
	ds_read_b128 v[114:117], v185 offset:45056
	ds_read_b128 v[118:121], v186 offset:45056
	ds_read_b128 v[106:109], v185 offset:47104
	ds_read_b128 v[110:113], v186 offset:47104
	ds_read_b128 v[98:101], v185 offset:49152
	ds_read_b128 v[102:105], v186 offset:49152
	s_waitcnt lgkmcnt(8)
	v_mfma_scale_f32_32x32x64_f8f6f4 v[66:81], v[222:229], v[130:137], v[66:81], v194, v193 op_sel_hi:[0,0,0]
	v_mov_b32_e32 v0, v219
	s_nop 1
	v_permlane32_swap_b32_e32 v219, v0
	v_add_f32_e32 v219, v219, v0
	v_fma_f32 v209, v209, v221, v219
	v_max_f32_e32 v177, v82, v83
	v_max3_f32 v177, v177, v84, v85
	v_max3_f32 v177, v177, v86, v87
	v_max3_f32 v177, v177, v88, v89
	v_max3_f32 v177, v177, v90, v91
	v_max3_f32 v177, v177, v92, v93
	v_max3_f32 v177, v177, v94, v95
	v_max3_f32 v177, v177, v96, v97
	s_waitcnt lgkmcnt(6)
	v_mfma_scale_f32_32x32x64_f8f6f4 v[50:65], v[246:253], v[122:129], v[50:65], v194, v194 op_sel_hi:[0,0,0]
	s_waitcnt lgkmcnt(4)
	v_mfma_scale_f32_32x32x64_f8f6f4 v[34:49], v[246:253], v[114:121], v[34:49], v194, v194 op_sel_hi:[0,0,0]
	s_waitcnt vmcnt(0)
	s_waitcnt lgkmcnt(0)
	s_barrier
	v_max_f32_e32 v0, v66, v67
	v_max3_f32 v0, v0, v68, v69
	v_max3_f32 v0, v0, v70, v71
	v_max3_f32 v0, v0, v72, v73
	s_waitcnt lgkmcnt(2)
	v_mfma_scale_f32_32x32x64_f8f6f4 v[18:33], v[246:253], v[106:113], v[18:33], v194, v194 op_sel_hi:[0,0,0]
	s_add_i32 m0, s98, 0xa800
	s_nop 0
	global_load_lds_dwordx4 v176, s[18:19]
	s_add_i32 m0, s98, 0xc800
	s_nop 0
	global_load_lds_dwordx4 v178, s[16:17]
	v_add_u32_e32 v176, 0x2000, v176
	v_add_u32_e32 v178, 0x20000, v178
	v_max3_f32 v0, v0, v74, v75
	v_max3_f32 v0, v0, v76, v77
	v_max3_f32 v0, v0, v78, v79
	v_max3_f32 v0, v0, v80, v81
	s_waitcnt lgkmcnt(0)
	v_mfma_scale_f32_32x32x64_f8f6f4 v[2:17], v[246:253], v[98:105], v[2:17], v194, v194 op_sel_hi:[0,0,0]
	v_max_f32_e32 v177, v177, v0
	v_mov_b32_e32 v0, v177
	v_mov_b32_e32 v218, 1.0
	s_nop 0
	v_permlane32_swap_b32_e32 v177, v0
	v_max_f32_e32 v177, v177, v0
	v_cmp_ge_f32_e32 vcc, s90, v177
	s_cmp_eq_u64 vcc, exec
	s_cbranch_scc0 .Lmla_s5_newmax
; __device__ __forceinline__ void finishSM9(f32x16& p0, f32x16& p1, float alpha, float& l_reg, v8i32& p8) {
; #pragma unroll
;   for (int r = 0; r < 16; ++r) { p0[r] = __builtin_amdgcn_exp2f(p0[r]); p1[r] = __builtin_amdgcn_exp2f(p1[r]); }
;   float ps = 0;
; #pragma unroll
;   for (int r = 0; r < 16; ++r) ps += p0[r];
; #pragma unroll
;   for (int r = 0; r < 16; ++r) ps += p1[r];
;   { auto rr = __builtin_amdgcn_permlane32_swap(__float_as_uint(ps), __float_as_uint(ps), false, false);
;     ps = __uint_as_float(rr[0]) + __uint_as_float(rr[1]); }
;   l_reg = l_reg * alpha + ps;
; #pragma unroll
;   for (int g = 0; g < 4; ++g) {
;     int w = __builtin_amdgcn_cvt_pk_fp8_f32(p0[4 * g], p0[4 * g + 1], 0, false); p8[g] = __builtin_amdgcn_cvt_pk_fp8_f32(p0[4 * g + 2], p0[4 * g + 3], w, true);
;     int u = __builtin_amdgcn_cvt_pk_fp8_f32(p1[4 * g], p1[4 * g + 1], 0, false); p8[4 + g] = __builtin_amdgcn_cvt_pk_fp8_f32(p1[4 * g + 2], p1[4 * g + 3], u, true); }
; }
; __device__ __forceinline__ void pv8(f32x16* o, const char* Vt, const v8i32 p8, int r32, int hi) {
;   const int sw = (r32 >> 2) & 3, a0 = r32 * 64 + (((hi * 2) ^ sw) << 4), a1 = r32 * 64 + (((hi * 2 + 1) ^ sw) << 4);
; #pragma unroll
;   for (int d0 = 0; d0 < 4; ++d0) {
;     const v8i32 vf = cat8(*reinterpret_cast<const v4i32*>(Vt + d0 * 2048 + a0), *reinterpret_cast<const v4i32*>(Vt + d0 * 2048 + a1));
;     o[d0] = __builtin_amdgcn_mfma_scale_f32_32x32x64_f8f6f4(p8, vf, o[d0], 0, 0, 0, 127, 0, 127); }
; }
; __device__ __forceinline__ void qkt9(f32x16& p0, f32x16& p1, const char* Kn, const char* Kr, const v8i32* qf, const float init, int r32, int hi) {
; #pragma unroll
;   for (int r = 0; r < 16; ++r) { p0[r] = init; p1[r] = init; }
; #pragma unroll
;   for (int s = 0; s < 2; ++s) { const int c0 = s * 4 + hi * 2;
;     const v8i32 a0 = cat8(*reinterpret_cast<const v4i32*>(Kn + KN8SW(r32, c0)), *reinterpret_cast<const v4i32*>(Kn + KN8SW(r32, c0 + 1)));
;     const v8i32 a1 = cat8(*reinterpret_cast<const v4i32*>(Kn + 4096 + KN8SW(r32, c0)), *reinterpret_cast<const v4i32*>(Kn + 4096 + KN8SW(r32, c0 + 1)));
;     p0 = __builtin_amdgcn_mfma_scale_f32_32x32x64_f8f6f4(a0, qf[s], p0, 0, 0, 0, 127, 0, 124);
;     p1 = __builtin_amdgcn_mfma_scale_f32_32x32x64_f8f6f4(a1, qf[s], p1, 0, 0, 0, 127, 0, 124); }
;   { const int c0 = hi * 2;
.Lmla_s5_cont:
	s_add_i32 s30, s30, 1
	s_cmpk_lt_u32 s30, 42
	s_cbranch_scc1 .Lmla_stag_loop
	ds_read_b128 v[114:117], v215 offset:24576
	ds_read_b128 v[118:121], v216 offset:24576
	ds_read_b128 v[222:225], v215 offset:28672
	ds_read_b128 v[226:229], v216 offset:28672
	s_waitcnt lgkmcnt(2)
	v_mfma_scale_f32_32x32x64_f8f6f4 v[114:129], v[114:121], v[146:153], v[230:245], v194, v193 op_sel_hi:[0,0,0]
	v_exp_f32_e32 v0, v82
	v_exp_f32_e32 v177, v83
	v_exp_f32_e32 v179, v84
	v_exp_f32_e32 v254, v85
	v_add_f32_e32 v219, v0, v177
	v_cvt_pk_fp8_f32 v246, v0, v177
	v_add_f32_e32 v219, v179, v219
	v_add_f32_e32 v219, v254, v219
	v_cvt_pk_fp8_f32 v246, v179, v254 op_sel:[0,0,1]
	v_exp_f32_e32 v0, v86
	v_exp_f32_e32 v177, v87
	v_exp_f32_e32 v179, v88
	v_exp_f32_e32 v254, v89
	v_add_f32_e32 v219, v0, v219
	v_add_f32_e32 v219, v177, v219
	v_cvt_pk_fp8_f32 v247, v0, v177
	v_add_f32_e32 v219, v179, v219
	v_add_f32_e32 v219, v254, v219
	v_cvt_pk_fp8_f32 v247, v179, v254 op_sel:[0,0,1]
	ds_read_b128 v[82:85], v213 offset:24576
	ds_read_b128 v[86:89], v214 offset:24576
	s_waitcnt lgkmcnt(2)
	v_mfma_scale_f32_32x32x64_f8f6f4 v[98:113], v[222:229], v[146:153], v[230:245], v194, v193 op_sel_hi:[0,0,0]
	ds_read_b128 v[222:225], v213 offset:28672
	ds_read_b128 v[226:229], v214 offset:28672
	v_exp_f32_e32 v0, v90
	v_exp_f32_e32 v177, v91
	v_exp_f32_e32 v179, v92
	v_exp_f32_e32 v254, v93
	v_add_f32_e32 v219, v0, v219
	v_add_f32_e32 v219, v177, v219
	v_cvt_pk_fp8_f32 v248, v0, v177
	v_add_f32_e32 v219, v179, v219
	v_add_f32_e32 v219, v254, v219
	v_cvt_pk_fp8_f32 v248, v179, v254 op_sel:[0,0,1]
	v_exp_f32_e32 v0, v94
	v_exp_f32_e32 v177, v95
	v_exp_f32_e32 v179, v96
	v_exp_f32_e32 v254, v97
	v_add_f32_e32 v219, v0, v219
	v_add_f32_e32 v219, v177, v219
	v_cvt_pk_fp8_f32 v249, v0, v177
	v_add_f32_e32 v219, v179, v219
	v_add_f32_e32 v219, v254, v219
	v_cvt_pk_fp8_f32 v249, v179, v254 op_sel:[0,0,1]
	ds_read_b128 v[90:93], v185 offset:36864
	ds_read_b128 v[94:97], v186 offset:36864
	s_waitcnt lgkmcnt(4)
	v_mfma_scale_f32_32x32x64_f8f6f4 v[114:129], v[82:89], v[138:145], v[114:129], v194, v193 op_sel_hi:[0,0,0]
	v_exp_f32_e32 v0, v66
	v_exp_f32_e32 v177, v67
	v_exp_f32_e32 v179, v68
	v_exp_f32_e32 v254, v69
	v_add_f32_e32 v219, v0, v219
	v_add_f32_e32 v219, v177, v219
	v_cvt_pk_fp8_f32 v250, v0, v177
	v_add_f32_e32 v219, v179, v219
	v_add_f32_e32 v219, v254, v219
	v_cvt_pk_fp8_f32 v250, v179, v254 op_sel:[0,0,1]
	s_waitcnt lgkmcnt(2)
	v_mfma_scale_f32_32x32x64_f8f6f4 v[98:113], v[222:229], v[138:145], v[98:113], v194, v193 op_sel_hi:[0,0,0]
	ds_read_b128 v[222:225], v185 offset:38912
	ds_read_b128 v[226:229], v186 offset:38912
	v_exp_f32_e32 v0, v70
	v_exp_f32_e32 v177, v71
	v_exp_f32_e32 v179, v72
	v_exp_f32_e32 v254, v73
	v_add_f32_e32 v219, v0, v219
	v_add_f32_e32 v219, v177, v219
	v_cvt_pk_fp8_f32 v251, v0, v177
	v_add_f32_e32 v219, v179, v219
	v_add_f32_e32 v219, v254, v219
	v_cvt_pk_fp8_f32 v251, v179, v254 op_sel:[0,0,1]
	v_exp_f32_e32 v0, v74
	v_exp_f32_e32 v177, v75
	v_exp_f32_e32 v179, v76
	v_exp_f32_e32 v254, v77
	v_add_f32_e32 v219, v0, v219
	v_add_f32_e32 v219, v177, v219
	v_cvt_pk_fp8_f32 v252, v0, v177
	v_add_f32_e32 v219, v179, v219
	v_add_f32_e32 v219, v254, v219
	v_cvt_pk_fp8_f32 v252, v179, v254 op_sel:[0,0,1]
	s_waitcnt lgkmcnt(2)
	v_mfma_scale_f32_32x32x64_f8f6f4 v[114:129], v[90:97], v[130:137], v[114:129], v194, v193 op_sel_hi:[0,0,0]
	v_exp_f32_e32 v0, v78
	v_exp_f32_e32 v177, v79
	v_exp_f32_e32 v179, v80
	v_exp_f32_e32 v254, v81
	v_add_f32_e32 v219, v0, v219
	v_add_f32_e32 v219, v177, v219
	v_cvt_pk_fp8_f32 v253, v0, v177
	v_add_f32_e32 v219, v179, v219
	v_add_f32_e32 v219, v254, v219
	v_cvt_pk_fp8_f32 v253, v179, v254 op_sel:[0,0,1]
	ds_read_b128 v[90:93], v185 offset:0
	ds_read_b128 v[94:97], v186 offset:0
	ds_read_b128 v[82:85], v185 offset:2048
	ds_read_b128 v[86:89], v186 offset:2048
	ds_read_b128 v[74:77], v185 offset:4096
	ds_read_b128 v[78:81], v186 offset:4096
	ds_read_b128 v[66:69], v185 offset:6144
	ds_read_b128 v[70:73], v186 offset:6144
	s_waitcnt lgkmcnt(8)
	v_mfma_scale_f32_32x32x64_f8f6f4 v[98:113], v[222:229], v[130:137], v[98:113], v194, v193 op_sel_hi:[0,0,0]
	v_mov_b32_e32 v0, v219
	s_nop 1
	v_permlane32_swap_b32_e32 v219, v0
	v_add_f32_e32 v219, v219, v0
	v_fma_f32 v209, v209, v218, v219
	v_max_f32_e32 v177, v114, v115
	v_max3_f32 v177, v177, v116, v117
	v_max3_f32 v177, v177, v118, v119
	v_max3_f32 v177, v177, v120, v121
	v_max3_f32 v177, v177, v122, v123
	v_max3_f32 v177, v177, v124, v125
	v_max3_f32 v177, v177, v126, v127
	v_max3_f32 v177, v177, v128, v129
	s_waitcnt lgkmcnt(6)
	v_mfma_scale_f32_32x32x64_f8f6f4 v[50:65], v[246:253], v[90:97], v[50:65], v194, v194 op_sel_hi:[0,0,0]
	s_waitcnt lgkmcnt(4)
	v_mfma_scale_f32_32x32x64_f8f6f4 v[34:49], v[246:253], v[82:89], v[34:49], v194, v194 op_sel_hi:[0,0,0]
	s_waitcnt vmcnt(0)
	s_waitcnt lgkmcnt(0)
	s_barrier
	v_max_f32_e32 v0, v98, v99
	v_max3_f32 v0, v0, v100, v101
	v_max3_f32 v0, v0, v102, v103
	v_max3_f32 v0, v0, v104, v105
	s_waitcnt lgkmcnt(2)
	v_mfma_scale_f32_32x32x64_f8f6f4 v[18:33], v[246:253], v[74:81], v[18:33], v194, v194 op_sel_hi:[0,0,0]
	s_add_i32 m0, s98, 0x0
	s_nop 0
	global_load_lds_dwordx4 v176, s[18:19]
	s_add_i32 m0, s98, 0x4000
	s_nop 0
	global_load_lds_dwordx4 v178, s[16:17]
	v_add_u32_e32 v176, 0x2000, v176
	v_add_u32_e32 v178, 0x20000, v178
	v_max3_f32 v0, v0, v106, v107
	v_max3_f32 v0, v0, v108, v109
	v_max3_f32 v0, v0, v110, v111
	v_max3_f32 v0, v0, v112, v113
	s_waitcnt lgkmcnt(0)
	v_mfma_scale_f32_32x32x64_f8f6f4 v[2:17], v[246:253], v[66:73], v[2:17], v194, v194 op_sel_hi:[0,0,0]
	v_max_f32_e32 v177, v177, v0
	v_mov_b32_e32 v0, v177
	v_mov_b32_e32 v221, 1.0
	s_nop 0
	v_permlane32_swap_b32_e32 v177, v0
	v_max_f32_e32 v177, v177, v0
	v_cmp_ge_f32_e32 vcc, s90, v177
	s_cmp_eq_u64 vcc, exec
	s_cbranch_scc0 .Lmla_q0_newmax
; __device__ __forceinline__ void finishSM9(f32x16& p0, f32x16& p1, float alpha, float& l_reg, v8i32& p8) {
; #pragma unroll
;   for (int r = 0; r < 16; ++r) { p0[r] = __builtin_amdgcn_exp2f(p0[r]); p1[r] = __builtin_amdgcn_exp2f(p1[r]); }
;   float ps = 0;
; #pragma unroll
;   for (int r = 0; r < 16; ++r) ps += p0[r];
; #pragma unroll
;   for (int r = 0; r < 16; ++r) ps += p1[r];
;   { auto rr = __builtin_amdgcn_permlane32_swap(__float_as_uint(ps), __float_as_uint(ps), false, false);
;     ps = __uint_as_float(rr[0]) + __uint_as_float(rr[1]); }
;   l_reg = l_reg * alpha + ps;
; #pragma unroll
;   for (int g = 0; g < 4; ++g) {
;     int w = __builtin_amdgcn_cvt_pk_fp8_f32(p0[4 * g], p0[4 * g + 1], 0, false); p8[g] = __builtin_amdgcn_cvt_pk_fp8_f32(p0[4 * g + 2], p0[4 * g + 3], w, true);
;     int u = __builtin_amdgcn_cvt_pk_fp8_f32(p1[4 * g], p1[4 * g + 1], 0, false); p8[4 + g] = __builtin_amdgcn_cvt_pk_fp8_f32(p1[4 * g + 2], p1[4 * g + 3], u, true); }
; }
; __device__ __forceinline__ void pv8(f32x16* o, const char* Vt, const v8i32 p8, int r32, int hi) {
;   const int sw = (r32 >> 2) & 3, a0 = r32 * 64 + (((hi * 2) ^ sw) << 4), a1 = r32 * 64 + (((hi * 2 + 1) ^ sw) << 4);
; #pragma unroll
;   for (int d0 = 0; d0 < 4; ++d0) {
;     const v8i32 vf = cat8(*reinterpret_cast<const v4i32*>(Vt + d0 * 2048 + a0), *reinterpret_cast<const v4i32*>(Vt + d0 * 2048 + a1));
;     o[d0] = __builtin_amdgcn_mfma_scale_f32_32x32x64_f8f6f4(p8, vf, o[d0], 0, 0, 0, 127, 0, 127); }
; }
; __device__ __forceinline__ void qkt9(f32x16& p0, f32x16& p1, const char* Kn, const char* Kr, const v8i32* qf, const float init, int r32, int hi) {
; #pragma unroll
;   for (int r = 0; r < 16; ++r) { p0[r] = init; p1[r] = init; }
; #pragma unroll
;   for (int s = 0; s < 2; ++s) { const int c0 = s * 4 + hi * 2;
;     const v8i32 a0 = cat8(*reinterpret_cast<const v4i32*>(Kn + KN8SW(r32, c0)), *reinterpret_cast<const v4i32*>(Kn + KN8SW(r32, c0 + 1)));
;     const v8i32 a1 = cat8(*reinterpret_cast<const v4i32*>(Kn + 4096 + KN8SW(r32, c0)), *reinterpret_cast<const v4i32*>(Kn + 4096 + KN8SW(r32, c0 + 1)));
;     p0 = __builtin_amdgcn_mfma_scale_f32_32x32x64_f8f6f4(a0, qf[s], p0, 0, 0, 0, 127, 0, 124);
;     p1 = __builtin_amdgcn_mfma_scale_f32_32x32x64_f8f6f4(a1, qf[s], p1, 0, 0, 0, 127, 0, 124); }
;   { const int c0 = hi * 2;
.Lmla_q0_cont:
	ds_read_b128 v[82:85], v215 offset:51200
	ds_read_b128 v[86:89], v216 offset:51200
	ds_read_b128 v[222:225], v215 offset:55296
	ds_read_b128 v[226:229], v216 offset:55296
	s_waitcnt lgkmcnt(2)
	v_mfma_scale_f32_32x32x64_f8f6f4 v[82:97], v[82:89], v[146:153], v[230:245], v194, v193 op_sel_hi:[0,0,0]
	v_exp_f32_e32 v0, v114
	v_exp_f32_e32 v177, v115
	v_exp_f32_e32 v179, v116
	v_exp_f32_e32 v254, v117
	v_add_f32_e32 v219, v0, v177
	v_cvt_pk_fp8_f32 v246, v0, v177
	v_add_f32_e32 v219, v179, v219
	v_add_f32_e32 v219, v254, v219
	v_cvt_pk_fp8_f32 v246, v179, v254 op_sel:[0,0,1]
	v_exp_f32_e32 v0, v118
	v_exp_f32_e32 v177, v119
	v_exp_f32_e32 v179, v120
	v_exp_f32_e32 v254, v121
	v_add_f32_e32 v219, v0, v219
	v_add_f32_e32 v219, v177, v219
	v_cvt_pk_fp8_f32 v247, v0, v177
	v_add_f32_e32 v219, v179, v219
	v_add_f32_e32 v219, v254, v219
	v_cvt_pk_fp8_f32 v247, v179, v254 op_sel:[0,0,1]
	ds_read_b128 v[114:117], v213 offset:51200
	ds_read_b128 v[118:121], v214 offset:51200
	s_waitcnt lgkmcnt(2)
	v_mfma_scale_f32_32x32x64_f8f6f4 v[66:81], v[222:229], v[146:153], v[230:245], v194, v193 op_sel_hi:[0,0,0]
	ds_read_b128 v[222:225], v213 offset:55296
	ds_read_b128 v[226:229], v214 offset:55296
	v_exp_f32_e32 v0, v122
	v_exp_f32_e32 v177, v123
	v_exp_f32_e32 v179, v124
	v_exp_f32_e32 v254, v125
	v_add_f32_e32 v219, v0, v219
	v_add_f32_e32 v219, v177, v219
	v_cvt_pk_fp8_f32 v248, v0, v177
	v_add_f32_e32 v219, v179, v219
	v_add_f32_e32 v219, v254, v219
	v_cvt_pk_fp8_f32 v248, v179, v254 op_sel:[0,0,1]
	v_exp_f32_e32 v0, v126
	v_exp_f32_e32 v177, v127
	v_exp_f32_e32 v179, v128
	v_exp_f32_e32 v254, v129
	v_add_f32_e32 v219, v0, v219
	v_add_f32_e32 v219, v177, v219
	v_cvt_pk_fp8_f32 v249, v0, v177
	v_add_f32_e32 v219, v179, v219
	v_add_f32_e32 v219, v254, v219
	v_cvt_pk_fp8_f32 v249, v179, v254 op_sel:[0,0,1]
	ds_read_b128 v[122:125], v185 offset:59392
	ds_read_b128 v[126:129], v186 offset:59392
	s_waitcnt lgkmcnt(4)
	v_mfma_scale_f32_32x32x64_f8f6f4 v[82:97], v[114:121], v[138:145], v[82:97], v194, v193 op_sel_hi:[0,0,0]
	v_exp_f32_e32 v0, v98
	v_exp_f32_e32 v177, v99
	v_exp_f32_e32 v179, v100
	v_exp_f32_e32 v254, v101
	v_add_f32_e32 v219, v0, v219
	v_add_f32_e32 v219, v177, v219
	v_cvt_pk_fp8_f32 v250, v0, v177
	v_add_f32_e32 v219, v179, v219
	v_add_f32_e32 v219, v254, v219
	v_cvt_pk_fp8_f32 v250, v179, v254 op_sel:[0,0,1]
	s_waitcnt lgkmcnt(2)
	v_mfma_scale_f32_32x32x64_f8f6f4 v[66:81], v[222:229], v[138:145], v[66:81], v194, v193 op_sel_hi:[0,0,0]
	ds_read_b128 v[222:225], v185 offset:61440
	ds_read_b128 v[226:229], v186 offset:61440
	v_exp_f32_e32 v0, v102
	v_exp_f32_e32 v177, v103
	v_exp_f32_e32 v179, v104
	v_exp_f32_e32 v254, v105
	v_add_f32_e32 v219, v0, v219
	v_add_f32_e32 v219, v177, v219
	v_cvt_pk_fp8_f32 v251, v0, v177
	v_add_f32_e32 v219, v179, v219
	v_add_f32_e32 v219, v254, v219
	v_cvt_pk_fp8_f32 v251, v179, v254 op_sel:[0,0,1]
	v_exp_f32_e32 v0, v106
	v_exp_f32_e32 v177, v107
	v_exp_f32_e32 v179, v108
	v_exp_f32_e32 v254, v109
	v_add_f32_e32 v219, v0, v219
	v_add_f32_e32 v219, v177, v219
	v_cvt_pk_fp8_f32 v252, v0, v177
	v_add_f32_e32 v219, v179, v219
	v_add_f32_e32 v219, v254, v219
	v_cvt_pk_fp8_f32 v252, v179, v254 op_sel:[0,0,1]
	s_waitcnt lgkmcnt(2)
	v_mfma_scale_f32_32x32x64_f8f6f4 v[82:97], v[122:129], v[130:137], v[82:97], v194, v193 op_sel_hi:[0,0,0]
	v_exp_f32_e32 v0, v110
	v_exp_f32_e32 v177, v111
	v_exp_f32_e32 v179, v112
	v_exp_f32_e32 v254, v113
	v_add_f32_e32 v219, v0, v219
	v_add_f32_e32 v219, v177, v219
	v_cvt_pk_fp8_f32 v253, v0, v177
	v_add_f32_e32 v219, v179, v219
	v_add_f32_e32 v219, v254, v219
	v_cvt_pk_fp8_f32 v253, v179, v254 op_sel:[0,0,1]
	ds_read_b128 v[122:125], v185 offset:8192
	ds_read_b128 v[126:129], v186 offset:8192
	ds_read_b128 v[114:117], v185 offset:10240
	ds_read_b128 v[118:121], v186 offset:10240
	ds_read_b128 v[106:109], v185 offset:12288
	ds_read_b128 v[110:113], v186 offset:12288
	ds_read_b128 v[98:101], v185 offset:14336
	ds_read_b128 v[102:105], v186 offset:14336
	s_waitcnt lgkmcnt(8)
	v_mfma_scale_f32_32x32x64_f8f6f4 v[66:81], v[222:229], v[130:137], v[66:81], v194, v193 op_sel_hi:[0,0,0]
	v_mov_b32_e32 v0, v219
	s_nop 1
	v_permlane32_swap_b32_e32 v219, v0
	v_add_f32_e32 v219, v219, v0
	v_fma_f32 v209, v209, v221, v219
	v_max_f32_e32 v177, v82, v83
	v_max3_f32 v177, v177, v84, v85
	v_max3_f32 v177, v177, v86, v87
	v_max3_f32 v177, v177, v88, v89
	v_max3_f32 v177, v177, v90, v91
	v_max3_f32 v177, v177, v92, v93
	v_max3_f32 v177, v177, v94, v95
	v_max3_f32 v177, v177, v96, v97
	s_waitcnt lgkmcnt(6)
	v_mfma_scale_f32_32x32x64_f8f6f4 v[50:65], v[246:253], v[122:129], v[50:65], v194, v194 op_sel_hi:[0,0,0]
	s_waitcnt lgkmcnt(4)
	v_mfma_scale_f32_32x32x64_f8f6f4 v[34:49], v[246:253], v[114:121], v[34:49], v194, v194 op_sel_hi:[0,0,0]
	s_waitcnt vmcnt(0)
	s_waitcnt lgkmcnt(0)
	s_barrier
	v_max_f32_e32 v0, v66, v67
	v_max3_f32 v0, v0, v68, v69
	v_max3_f32 v0, v0, v70, v71
	v_max3_f32 v0, v0, v72, v73
	s_waitcnt lgkmcnt(2)
	v_mfma_scale_f32_32x32x64_f8f6f4 v[18:33], v[246:253], v[106:113], v[18:33], v194, v194 op_sel_hi:[0,0,0]
	v_max3_f32 v0, v0, v74, v75
	v_max3_f32 v0, v0, v76, v77
	v_max3_f32 v0, v0, v78, v79
	v_max3_f32 v0, v0, v80, v81
	s_waitcnt lgkmcnt(0)
	v_mfma_scale_f32_32x32x64_f8f6f4 v[2:17], v[246:253], v[98:105], v[2:17], v194, v194 op_sel_hi:[0,0,0]
	v_max_f32_e32 v177, v177, v0
	v_mov_b32_e32 v0, v177
	v_mov_b32_e32 v218, 1.0
	s_nop 0
	v_permlane32_swap_b32_e32 v177, v0
	v_max_f32_e32 v177, v177, v0
	v_cmp_ge_f32_e32 vcc, s90, v177
	s_cmp_eq_u64 vcc, exec
	s_cbranch_scc0 .Lmla_q1_newmax
